# M1: gate section of the two gate waves moved after all of the round's loads are issued (temporaries renamed to dead registers, gate inputs prefetched a round ahead), so those waves no longer lag the r
# baseline (speedup 1.0000x reference)
; __device__ __forceinline__ void m1_phase(const Params& p, unsigned char* ldsg, int G) {
;     const int tid = threadIdx.x, lane = tid & 63, wave = __builtin_amdgcn_readfirstlane(tid >> 6), fr = lane & 15, fq = lane >> 4;
;     const int half = wave >> 2, hw = wave & 3, htid = tid & 255;
;     unsigned char* ws = p.ws;
;     const bf16* PROJ = (const bf16*)(ws + WS_HB); const float* GATES = (const float*)(ws + WS_GATES);
;     bf16* DCB = (bf16*)p.out; bf16* QKC = (bf16*)((unsigned char*)p.out + 32 * MiB); float* DN = (float*)(ws + WS_DN); float* GARR = (float*)(ws + WS_SC); float* AMAXARR = GARR + 1024;
;     bf16* KT = (bf16*)(ldsg + half * 40960); bf16* VT = KT + 128 * TP; float* sW = (float*)(ldsg + half * 40960 + 36864);
;     for (int r = blockIdx.x; r < NCH * NH / 2; r += G) {
;         const int c = r >> 1, h = 2 * (r & 1) + half, u = c * 4 + h, t0 = c * CL;
;         if (hw == 0) {
;             const float ig = GATES[(size_t)(t0 + lane) * 8 + h], fp = GATES[(size_t)(t0 + lane) * 8 + 4 + h];
.LBB0_608:
	s_or_b64 exec, exec, s[0:1]
	s_add_u32 s56, s70, 0x2000000
	s_addc_u32 s57, s71, 0
	s_add_u32 s34, s72, 0x500000
	s_addc_u32 s35, s73, 0
	s_add_u32 s36, s72, 0x501000
	v_lshrrev_b32_e32 v159, 4, v153
	s_addc_u32 s37, s73, 0
	v_readfirstlane_b32 s0, v240
	s_cmpk_gt_i32 s86, 0x1ff
	v_cmp_gt_u32_e64 s[8:9], 2, v153
	v_cmp_gt_u32_e64 s[10:11], 4, v153
	v_cmp_gt_u32_e64 s[12:13], 8, v153
	v_cmp_gt_u32_e64 s[14:15], 32, v153
	v_lshlrev_b32_e32 v92, 3, v159
	v_lshlrev_b32_e32 v167, 8, v152
	v_and_b32_e32 v157, 8, v152
	s_waitcnt lgkmcnt(0)
	s_barrier
	s_cbranch_scc1 .LBB0_648
	s_ashr_i32 s2, s0, 2
	v_and_b32_e32 v64, 0x78, v230
	s_mul_i32 s1, s2, 0xa000
	v_mov_b32_e32 v67, 0
	v_lshlrev_b32_e32 v66, 1, v64
	v_and_b32_e32 v0, 56, v230
	s_add_i32 s1, s1, 0
	v_and_b32_e32 v2, 0xff, v152
	v_lshl_add_u64 v[68:69], s[56:57], 0, v[66:67]
	v_bitop3_b32 v0, v175, v0, 60 bitop3:0x6c
	v_and_b32_e32 v66, 0x100, v167
	s_and_b32 s3, s0, 3
	v_and_b32_e32 v118, 60, v175
	v_lshl_add_u32 v4, v0, 1, s1
	v_lshl_add_u64 v[0:1], s[70:71], 0, v[66:67]
	v_mov_b32_e32 v93, v67
	s_movk_i32 s0, 0x80
	v_lshlrev_b32_e32 v66, 2, v2
	v_mov_b32_e32 v3, s1
	v_lshl_add_u32 v65, v153, 2, s1
	v_lshl_add_u32 v120, v118, 2, s1
	v_lshl_or_b32 v5, s3, 5, v234
	v_lshl_add_u64 v[70:71], v[0:1], 0, v[92:93]
	v_cmp_gt_u32_e64 s[20:21], s0, v2
	s_movk_i32 s6, 0x90
	v_lshl_add_u64 v[0:1], s[72:73], 0, v[66:67]
	s_mov_b64 s[0:1], 0x480000
	v_mad_u32_u24 v93, v2, s6, v3
	v_lshl_add_u64 v[72:73], v[0:1], 0, s[0:1]
	v_mad_u32_u24 v1, v5, s6, v3
	v_bitop3_b32 v2, v5, v92, 40 bitop3:0x6c
	v_lshl_add_u32 v121, v2, 1, v1
	v_or_b32_e32 v2, 32, v92
	v_bitop3_b32 v7, v5, v2, 40 bitop3:0x6c
	v_or_b32_e32 v5, 16, v5
	v_lshl_add_u32 v122, v7, 1, v1
	v_add_u32_e32 v1, 0x900, v1
	v_bitop3_b32 v7, v5, v92, 56 bitop3:0x6c
	v_bitop3_b32 v2, v5, v2, 56 bitop3:0x6c
	v_lshl_add_u32 v123, v7, 1, v1
	v_lshl_add_u32 v124, v2, 1, v1
	v_mad_u32_u24 v1, v234, s6, v3
	v_bitop3_b32 v2, v92, v152, 8 bitop3:0x78
	v_lshlrev_b32_e32 v6, 7, v152
	v_lshl_add_u32 v125, v2, 1, v1
	v_bitop3_b32 v2, v92, v157, 32 bitop3:0x36
	v_lshl_add_u32 v126, v2, 1, v1
	v_and_b32_e32 v2, 0x700, v6
	v_lshl_or_b32 v127, s3, 12, v2
	v_or_b32_e32 v2, 16, v234
	v_bitop3_b32 v3, v234, 24, 16 bitop3:0xc8
	v_bitop3_b32 v2, v92, v2, 24 bitop3:0x78
	v_bitop3_b32 v3, v92, v3, 32 bitop3:0x36
	v_add_u32_e32 v5, 0x900, v1
	v_lshlrev_b32_e32 v2, 1, v2
	v_lshlrev_b32_e32 v3, 1, v3
	v_add_u32_e32 v129, v5, v2
	v_add_u32_e32 v130, v5, v3
	v_or_b32_e32 v5, 32, v234
	v_bitop3_b32 v6, v234, 40, 32 bitop3:0xc8
	v_bitop3_b32 v5, v92, v5, 40 bitop3:0x78
	v_bitop3_b32 v6, v92, v6, 32 bitop3:0x36
	v_add_u32_e32 v7, 0x1200, v1
	v_lshlrev_b32_e32 v5, 1, v5
	v_lshlrev_b32_e32 v6, 1, v6
	v_add_u32_e32 v131, v7, v5
	v_add_u32_e32 v132, v7, v6
	v_or_b32_e32 v7, 48, v234
	v_bitop3_b32 v8, v234, 56, 48 bitop3:0xc8
	v_bitop3_b32 v7, v92, v7, 56 bitop3:0x78
	v_bitop3_b32 v8, v92, v8, 32 bitop3:0x36
	v_mul_u32_u24_e32 v0, 0x90, v64
	v_add_u32_e32 v9, 0x1b00, v1
	v_lshlrev_b32_e32 v7, 1, v7
	v_lshlrev_b32_e32 v8, 1, v8
	v_add_u32_e32 v133, v9, v7
	v_add_u32_e32 v134, v9, v8
	v_add_u32_e32 v9, 0x2d00, v1
	v_add_u32_e32 v142, v4, v0
	v_mbcnt_lo_u32_b32 v0, -1, 0
	s_cmp_eq_u32 s3, 0
	v_add_u32_e32 v135, v9, v2
	v_add_u32_e32 v2, 0x3600, v1
	v_add_u32_e32 v1, 0x3f00, v1
	v_mbcnt_hi_u32_b32 v144, -1, v0
	v_bfrev_b32_e32 v0, 0.5
	s_cselect_b64 s[4:5], -1, 0
	v_cmp_eq_u32_e64 s[16:17], 0, v153
	v_cmp_gt_u32_e64 s[18:19], 16, v153
	v_or_b32_e32 v119, 0x200, v64
	v_or_b32_e32 v128, 0x800, v127
	v_add_u32_e32 v136, v9, v3
	v_add_u32_e32 v137, v2, v5
	v_add_u32_e32 v138, v2, v6
	v_add_u32_e32 v139, v1, v7
	v_add_u32_e32 v140, v1, v8
	s_mov_b32 s3, 0xbfb8aa3b
	v_mov_b32_e32 v141, 0x3ecc95a3
	s_mov_b32 s33, 0x3f317218
	s_mov_b32 s43, 0x33800000
	s_mov_b32 s46, 0x3fb8aa3b
	s_mov_b32 s47, 0xc2ce8ed0
	s_mov_b32 s62, 0x42b17218
	s_movk_i32 s63, 0x1600
	s_mov_b32 s64, 0xffff0000
	s_mov_b64 s[6:7], 0x1000
	s_mov_b64 s[38:39], 0x2000
	s_movk_i32 s65, 0x2000
	s_mov_b64 s[40:41], 0x3000
	s_movk_i32 s80, 0x3000
	s_movk_i32 s81, 0x7fff
	s_mov_b32 s42, 0x3db504f3
	v_lshlrev_b32_e32 v66, 1, v64
	v_mov_b32_e32 v143, 0x7f800000
	v_lshl_or_b32 v145, v144, 2, v0
	v_mov_b32_e32 v146, 1
	s_mov_b32 s82, s86
	s_andn2_b64 vcc, exec, s[4:5]
	s_cbranch_vccnz .Lm1pf_skip_0
	s_lshl_b32 s0, s82, 1
	s_ashr_i32 s83, s82, 1
	s_and_b32 s0, s0, 2
	s_add_i32 s44, s0, s2
	s_lshl_b32 s22, s83, 6
	v_or_b32_e32 v186, s22, v153
	v_ashrrev_i32_e32 v187, 31, v186
	v_lshlrev_b64 v[186:187], 5, v[186:187]
	s_ashr_i32 s45, s44, 31
	v_lshl_add_u64 v[186:187], s[54:55], 0, v[186:187]
	v_lshl_add_u64 v[186:187], s[44:45], 2, v[186:187]
	global_load_dword v228, v[186:187], off offset:16
	global_load_dword v229, v[186:187], off

; __device__ __forceinline__ void m1_phase(const Params& p, unsigned char* ldsg, int G) {
;     ...
;     for (int r = blockIdx.x; r < NCH * NH / 2; r += G) {
;         const int c = r >> 1, h = 2 * (r & 1) + half, u = c * 4 + h, t0 = c * CL;
;         if (hw == 0) {
;             const float ig = GATES[(size_t)(t0 + lane) * 8 + h], fp = GATES[(size_t)(t0 + lane) * 8 + 4 + h];
.LBB0_610:
	s_or_b64 exec, exec, s[0:1]
	s_add_i32 s82, s82, s74
	s_cmpk_gt_i32 s82, 0x1ff
	s_cbranch_scc1 .Lm1pf_skip_1
	s_andn2_b64 vcc, exec, s[4:5]
	s_cbranch_vccnz .Lm1pf_skip_1
	s_lshl_b32 s0, s82, 1
	s_ashr_i32 s83, s82, 1
	s_and_b32 s0, s0, 2
	s_add_i32 s44, s0, s2
	s_lshl_b32 s22, s83, 6
	v_or_b32_e32 v186, s22, v153
	v_ashrrev_i32_e32 v187, 31, v186
	v_lshlrev_b64 v[186:187], 5, v[186:187]
	s_ashr_i32 s45, s44, 31
	v_lshl_add_u64 v[186:187], s[54:55], 0, v[186:187]
	v_lshl_add_u64 v[186:187], s[44:45], 2, v[186:187]
	global_load_dword v228, v[186:187], off offset:16
	global_load_dword v229, v[186:187], off

; __device__ __forceinline__ float log_sigmoid_f(float x) { return fminf(x, 0.f) - log1pf(expf(-fabsf(x))); }
; __device__ __forceinline__ void m1_phase(const Params& p, unsigned char* ldsg, int G) {
;     ...
;         const int c = r >> 1, h = 2 * (r & 1) + half, u = c * 4 + h, t0 = c * CL;
;         if (hw == 0) {
;             const float ig = GATES[(size_t)(t0 + lane) * 8 + h], fp = GATES[(size_t)(t0 + lane) * 8 + 4 + h];
;             const float b = wave_incl_sum(log_sigmoid_f(fp), lane);
;             const float g = __shfl(b, 63);
;             const float a = g - b + ig;
;             const float amax = wave_max(a);
;             sW[lane] = expf(a - amax);
;             if (lane == 0) { GARR[h * NCH + c] = g; AMAXARR[h * NCH + c] = amax; }
;         }
.LBB0_611:
	s_lshl_b32 s0, s82, 1
	s_ashr_i32 s83, s82, 1
	s_and_b32 s0, s0, 2
	s_add_i32 s44, s0, s2
	s_lshl_b32 s22, s83, 6

; __device__ __forceinline__ void conv4x8(const bf16* proj, int t, int ch, const float* cw, const float* cb, float sc, float (&o)[4][8]) {
;     u32x4 raw[7];
; #pragma unroll
;     for (int i = 0; i < 7; ++i) { const int tr = t - 3 + i; raw[i] = tr >= 0 ? *(const u32x4*)(proj + (size_t)tr * NPROJ + ch) : (u32x4){0u, 0u, 0u, 0u}; }
;     { const f32x4 b0 = *(const f32x4*)(cb + ch), b1 = *(const f32x4*)(cb + ch + 4);
; #pragma unroll
;       for (int j = 0; j < 4; ++j) { o[j][0] = b0[0]; o[j][1] = b0[1]; o[j][2] = b0[2]; o[j][3] = b0[3]; o[j][4] = b1[0]; o[j][5] = b1[1]; o[j][6] = b1[2]; o[j][7] = b1[3]; } }
; #pragma unroll
;     for (int w = 0; w < 4; ++w) {
;         const f32x4 w0 = *(const f32x4*)(cw + w * 1024 + ch), w1 = *(const f32x4*)(cw + w * 1024 + ch + 4);
;         const float wv[8] = {w0[0], w0[1], w0[2], w0[3], w1[0], w1[1], w1[2], w1[3]};
; __device__ __forceinline__ void m1_phase(const Params& p, unsigned char* ldsg, int G) {
;     ...
;             u32x4 rv[4];
; #pragma unroll
;             for (int j = 0; j < 4; ++j) rv[j] = *(const u32x4*)(PROJ + (size_t)(t0 + l0 + j) * NPROJ + 1024 + h * HD + cgp * 8);
.LBB0_630:
	s_or_b64 exec, exec, s[0:1]
	v_lshlrev_b64 v[10:11], 2, v[6:7]
	v_lshl_add_u64 v[12:13], s[50:51], 0, v[10:11]
	v_lshl_add_u64 v[42:43], s[48:49], 0, v[10:11]
	global_load_dwordx4 v[6:9], v[12:13], off offset:16
	global_load_dwordx4 v[14:17], v[12:13], off
	s_nop 0
	global_load_dwordx4 v[10:13], v[42:43], off offset:16
	global_load_dwordx4 v[18:21], v[42:43], off
	s_waitcnt vmcnt(4)
	v_lshlrev_b32_e32 v98, 16, v26
	v_and_b32_e32 v100, 0xffff0000, v26
	v_add_co_u32_e64 v26, s[0:1], s65, v42
	v_lshlrev_b32_e32 v99, 16, v27
	v_and_b32_e32 v101, 0xffff0000, v27
	v_lshlrev_b32_e32 v96, 16, v22
	v_and_b32_e32 v94, 0xffff0000, v22
	v_lshlrev_b32_e32 v97, 16, v23
	v_and_b32_e32 v95, 0xffff0000, v23
	v_lshl_add_u64 v[22:23], v[42:43], 0, s[6:7]
	v_addc_co_u32_e64 v27, s[0:1], 0, v43, s[0:1]
	v_lshlrev_b32_e32 v103, 16, v29
	v_lshlrev_b32_e32 v102, 16, v28
	v_and_b32_e32 v83, 0xffff0000, v29
	v_and_b32_e32 v82, 0xffff0000, v28
	v_lshlrev_b32_e32 v90, 16, v24
	v_and_b32_e32 v84, 0xffff0000, v24
	v_lshlrev_b32_e32 v91, 16, v25
	v_and_b32_e32 v85, 0xffff0000, v25
	global_load_dwordx4 v[34:37], v[26:27], off offset:-4096
	s_nop 0
	global_load_dwordx4 v[22:25], v[22:23], off offset:16
	v_lshl_add_u64 v[28:29], v[42:43], 0, s[38:39]
	v_lshl_add_u64 v[44:45], v[42:43], 0, s[40:41]
	v_add_co_u32_e64 v42, s[0:1], s80, v42
	global_load_dwordx4 v[38:41], v[26:27], off
	s_nop 0
	global_load_dwordx4 v[26:29], v[28:29], off offset:16
	v_addc_co_u32_e64 v43, s[0:1], 0, v43, s[0:1]
	global_load_dwordx4 v[46:49], v[42:43], off
	s_nop 0
	global_load_dwordx4 v[42:45], v[44:45], off offset:16
	s_ashr_i32 s59, s58, 31
	v_lshl_add_u64 v[62:63], s[58:59], 1, v[68:69]
	v_add_u32_e32 v248, s58, v119
	v_ashrrev_i32_e32 v249, 31, v248
	v_lshl_add_u64 v[248:249], v[248:249], 1, s[78:79]
	v_cmp_lt_i32_e64 s[98:99], 2, v74
	v_mov_b32_e32 v188, 0
	v_mov_b32_e32 v189, 0
	v_mov_b32_e32 v190, 0
	v_mov_b32_e32 v191, 0
	v_mov_b32_e32 v192, 0
	v_mov_b32_e32 v193, 0
	v_mov_b32_e32 v194, 0
	v_mov_b32_e32 v195, 0
	v_mov_b32_e32 v196, 0
	v_mov_b32_e32 v197, 0
	v_mov_b32_e32 v198, 0
	v_mov_b32_e32 v199, 0
	v_mov_b32_e32 v200, 0
	v_mov_b32_e32 v201, 0
	v_mov_b32_e32 v202, 0
	v_mov_b32_e32 v203, 0
	v_mov_b32_e32 v204, 0
	v_mov_b32_e32 v205, 0
	v_mov_b32_e32 v206, 0
	v_mov_b32_e32 v207, 0
	v_mov_b32_e32 v208, 0
	v_mov_b32_e32 v209, 0
	v_mov_b32_e32 v210, 0
	v_mov_b32_e32 v211, 0
	v_mov_b32_e32 v212, 0
	v_mov_b32_e32 v213, 0
	v_mov_b32_e32 v214, 0
	v_mov_b32_e32 v215, 0
	s_and_saveexec_b64 s[100:101], s[98:99]
	v_mad_u64_u32 v[238:239], s[84:85], v110, s63, v[248:249]
	global_load_dwordx4 v[188:191], v[238:239], off
	s_or_b64 exec, exec, s[100:101]
	s_and_saveexec_b64 s[100:101], s[22:23]
	v_mad_u64_u32 v[238:239], s[84:85], v111, s63, v[248:249]
	global_load_dwordx4 v[192:195], v[238:239], off
	s_or_b64 exec, exec, s[100:101]
	s_and_saveexec_b64 s[100:101], s[24:25]
	v_mad_u64_u32 v[238:239], s[84:85], v112, s63, v[248:249]
	global_load_dwordx4 v[196:199], v[238:239], off
	s_or_b64 exec, exec, s[100:101]
	s_and_saveexec_b64 s[100:101], s[60:61]
	v_mad_u64_u32 v[238:239], s[84:85], v74, s63, v[248:249]
	global_load_dwordx4 v[200:203], v[238:239], off
	s_or_b64 exec, exec, s[100:101]
	s_and_saveexec_b64 s[100:101], s[26:27]
	v_mad_u64_u32 v[238:239], s[84:85], v76, s63, v[248:249]
	global_load_dwordx4 v[204:207], v[238:239], off
	s_or_b64 exec, exec, s[100:101]
	s_and_saveexec_b64 s[100:101], s[28:29]
	v_mad_u64_u32 v[238:239], s[84:85], v78, s63, v[248:249]
	global_load_dwordx4 v[208:211], v[238:239], off
	s_or_b64 exec, exec, s[100:101]
	s_and_saveexec_b64 s[100:101], s[30:31]
	v_mad_u64_u32 v[238:239], s[84:85], v80, s63, v[248:249]
	global_load_dwordx4 v[212:215], v[238:239], off
	s_or_b64 exec, exec, s[100:101]
	v_lshl_add_u64 v[248:249], s[58:59], 1, v[66:67]
	v_lshl_add_u64 v[248:249], v[248:249], 0, s[78:79]
	v_mad_u64_u32 v[238:239], s[84:85], v74, s63, v[248:249]
	global_load_dwordx4 v[216:219], v[238:239], off offset:2048
	v_mad_u64_u32 v[238:239], s[84:85], v76, s63, v[248:249]
	global_load_dwordx4 v[220:223], v[238:239], off offset:2048
	v_mad_u64_u32 v[238:239], s[84:85], v78, s63, v[248:249]
	global_load_dwordx4 v[224:227], v[238:239], off offset:2048
	v_mad_u64_u32 v[238:239], s[84:85], v80, s63, v[248:249]
	global_load_dwordx4 v[250:253], v[238:239], off offset:2048
	s_andn2_b64 vcc, exec, s[4:5]
	s_cbranch_vccnz .Lm1gate_skip
; __device__ __forceinline__ float log_sigmoid_f(float x) { return fminf(x, 0.f) - log1pf(expf(-fabsf(x))); }
; __device__ __forceinline__ void m1_phase(const Params& p, unsigned char* ldsg, int G) {
;     ...
;         if (hw == 0) {
;             const float ig = GATES[(size_t)(t0 + lane) * 8 + h], fp = GATES[(size_t)(t0 + lane) * 8 + 4 + h];
;             const float b = wave_incl_sum(log_sigmoid_f(fp), lane);
;             const float g = __shfl(b, 63);
;             const float a = g - b + ig;
;             const float amax = wave_max(a);
;             sW[lane] = expf(a - amax);
;             if (lane == 0) { GARR[h * NCH + c] = g; AMAXARR[h * NCH + c] = amax; }
;         }
	s_waitcnt vmcnt(14)
	v_mov_b32_e32 v178, v228
	v_mov_b32_e32 v181, v229
	v_mov_b32_e32 v161, 0xb2a5705f
	v_and_b32_e32 v179, 64, v144
	v_add_u32_e32 v180, -1, v144
	v_mov_b32_e32 v163, 0x42ce8ed0
	v_cmp_lt_i32_e32 vcc, v180, v179
	v_mov_b32_e32 v169, 0xc2b17218
	v_mov_b32_e32 v171, 0x3f2aaaab
	v_cndmask_b32_e32 v180, v180, v144, vcc
	v_mov_b32_e32 v175, 0x7f800000
	v_lshlrev_b32_e32 v180, 2, v180
	v_mul_f32_e64 v176, |v178|, s3
	v_fma_f32 v177, |v178|, s3, -v176
	v_rndne_f32_e32 v182, v176
	v_fma_f32 v177, |v178|, v161, v177
	v_sub_f32_e32 v176, v176, v182
	v_add_f32_e32 v176, v176, v177
	v_cvt_i32_f32_e32 v182, v182
	v_exp_f32_e32 v176, v176
	v_cmp_ngt_f32_e64 vcc, |v178|, v163
	v_max_f32_e32 v177, v178, v178
	v_min_f32_e32 v183, 0, v177
	v_ldexp_f32 v176, v176, v182
	v_cndmask_b32_e32 v176, 0, v176, vcc
	v_cmp_nlt_f32_e64 vcc, |v178|, v169
	s_nop 1
	v_cndmask_b32_e32 v178, v143, v176, vcc
	v_add_f32_e32 v182, 1.0, v178
	v_add_f32_e32 v184, -1.0, v182
	v_frexp_mant_f32_e32 v185, v182
	v_cvt_f64_f32_e32 v[176:177], v182
	v_sub_f32_e32 v186, v184, v182
	v_frexp_exp_i32_f64_e32 v176, v[176:177]
	v_cmp_gt_f32_e32 vcc, v171, v185
	v_sub_f32_e32 v184, v178, v184
	v_add_f32_e32 v177, 1.0, v186
	v_subbrev_co_u32_e32 v176, vcc, 0, v176, vcc
	v_add_f32_e32 v177, v184, v177
	v_sub_u32_e32 v184, 0, v176
	v_cvt_f32_i32_e32 v176, v176
	v_ldexp_f32 v182, v182, v184
	v_ldexp_f32 v177, v177, v184
	v_add_f32_e32 v184, -1.0, v182
	v_add_f32_e32 v185, 1.0, v182
	v_add_f32_e32 v186, 1.0, v184
	v_add_f32_e32 v187, -1.0, v185
	v_sub_f32_e32 v186, v182, v186
	v_sub_f32_e32 v182, v182, v187
	v_mul_f32_e32 v187, 0x3f317218, v176
	v_add_f32_e32 v186, v177, v186
	v_add_f32_e32 v177, v177, v182
	v_fma_f32 v182, v176, s33, -v187
	v_add_f32_e32 v147, v184, v186
	v_add_f32_e32 v148, v185, v177
	v_fmac_f32_e32 v182, 0xb102e308, v176
	v_sub_f32_e32 v176, v184, v147
	v_sub_f32_e32 v184, v185, v148
	v_rcp_f32_e32 v185, v148
	v_add_f32_e32 v149, v187, v182
	v_add_f32_e32 v177, v177, v184
	v_sub_f32_e32 v184, v149, v187
	v_sub_f32_e32 v182, v182, v184
	v_mul_f32_e32 v184, v147, v185
	v_add_f32_e32 v176, v186, v176
	v_mul_f32_e32 v186, v148, v184
	v_fma_f32 v187, v184, v148, -v186
	v_fmac_f32_e32 v187, v184, v177
	v_add_f32_e32 v150, v186, v187
	v_sub_f32_e32 v151, v147, v150
	v_sub_f32_e32 v186, v150, v186
	v_sub_f32_e32 v147, v147, v151
	v_sub_f32_e32 v186, v186, v187
	v_sub_f32_e32 v187, v147, v150
	v_add_f32_e32 v176, v176, v187
	v_add_f32_e32 v176, v186, v176
	v_add_f32_e32 v186, v151, v176
	v_mul_f32_e32 v187, v185, v186
	v_sub_f32_e32 v147, v151, v186
	v_mul_f32_e32 v150, v148, v187
	v_add_f32_e32 v176, v176, v147
	v_add_f32_e32 v147, v184, v187
	v_fma_f32 v148, v187, v148, -v150
	v_sub_f32_e32 v184, v147, v184
	v_fmac_f32_e32 v148, v187, v177
	v_sub_f32_e32 v177, v187, v184
	v_add_f32_e32 v184, v150, v148
	v_sub_f32_e32 v187, v184, v150
	v_sub_f32_e32 v150, v186, v184
	v_sub_f32_e32 v186, v186, v150
	v_sub_f32_e32 v184, v186, v184
	v_sub_f32_e32 v187, v187, v148
	v_add_f32_e32 v176, v176, v184
	v_add_f32_e32 v176, v187, v176
	v_add_f32_e32 v176, v150, v176
	v_mul_f32_e32 v176, v185, v176
	v_add_f32_e32 v176, v177, v176
	v_add_f32_e32 v177, v147, v176
	v_mul_f32_e32 v184, v177, v177
	v_fmamk_f32 v187, v184, 0x3e9b6dac, v141
	v_sub_f32_e32 v185, v177, v147
	v_ldexp_f32 v186, v177, 1
	v_mul_f32_e32 v177, v177, v184
	v_fmaak_f32 v184, v184, v187, 0x3f2aaada
	v_mul_f32_e32 v177, v177, v184
	v_add_f32_e32 v184, v186, v177
	v_sub_f32_e32 v176, v176, v185
	v_sub_f32_e32 v185, v184, v186
	v_ldexp_f32 v176, v176, 1
	v_sub_f32_e32 v177, v177, v185
	v_add_f32_e32 v176, v176, v177
	v_add_f32_e32 v177, v184, v176
	v_sub_f32_e32 v184, v177, v184
	v_add_f32_e32 v185, v149, v177
	v_sub_f32_e32 v176, v176, v184
	v_sub_f32_e32 v184, v185, v149
	v_sub_f32_e32 v186, v185, v184
	v_sub_f32_e32 v177, v177, v184
	v_add_f32_e32 v184, v182, v176
	v_sub_f32_e32 v186, v149, v186
	v_sub_f32_e32 v187, v184, v182
	v_add_f32_e32 v177, v177, v186
	v_sub_f32_e32 v186, v184, v187
	v_sub_f32_e32 v176, v176, v187
	v_sub_f32_e32 v182, v182, v186
	v_add_f32_e32 v177, v184, v177
	v_add_f32_e32 v176, v176, v182
	v_add_f32_e32 v182, v185, v177
	v_sub_f32_e32 v184, v182, v185
	v_sub_f32_e32 v177, v177, v184
	v_add_f32_e32 v176, v176, v177
	v_add_f32_e32 v176, v182, v176
	v_cmp_neq_f32_e32 vcc, v175, v178
	s_nop 1
	v_cndmask_b32_e32 v176, v143, v176, vcc
	v_cmp_lt_f32_e64 vcc, |v178|, s43
	s_nop 1
	v_cndmask_b32_e32 v176, v176, v178, vcc
	v_sub_f32_e32 v176, v183, v176
	s_nop 1
	v_add_f32_dpp v176, v176, v176 row_shr:1 row_mask:0xf bank_mask:0xf bound_ctrl:0
	s_nop 1
	v_add_f32_dpp v176, v176, v176 row_shr:2 row_mask:0xf bank_mask:0xf bound_ctrl:0
	s_nop 1
	v_add_f32_dpp v176, v176, v176 row_shr:4 row_mask:0xf bank_mask:0xf bound_ctrl:0
	s_nop 1
	v_add_f32_dpp v176, v176, v176 row_shr:8 row_mask:0xf bank_mask:0xf bound_ctrl:0
	s_nop 1
	v_add_f32_dpp v176, v176, v176 row_bcast:15 row_mask:0xa bank_mask:0xf
	s_nop 1
	v_add_f32_dpp v176, v176, v176 row_bcast:31 row_mask:0xc bank_mask:0xf
	s_nop 1
	v_readlane_b32 s98, v176, 63
	s_nop 1
	v_sub_f32_e32 v177, s98, v176
	v_add_f32_e32 v180, v181, v177
	v_mov_b32_e32 v177, v180
	s_nop 1
	v_max_f32_dpp v177, v177, v177 row_shr:1 row_mask:0xf bank_mask:0xf
	s_nop 1
	v_max_f32_dpp v177, v177, v177 row_shr:2 row_mask:0xf bank_mask:0xf
	s_nop 1
	v_max_f32_dpp v177, v177, v177 row_shr:4 row_mask:0xf bank_mask:0xf
	s_nop 1
	v_max_f32_dpp v177, v177, v177 row_shr:8 row_mask:0xf bank_mask:0xf
	s_nop 1
	v_max_f32_dpp v177, v177, v177 row_bcast:15 row_mask:0xa bank_mask:0xf
	s_nop 1
	v_max_f32_dpp v177, v177, v177 row_bcast:31 row_mask:0xc bank_mask:0xf
	s_nop 1
	v_readlane_b32 s99, v177, 63
	s_nop 2
	v_mov_b32_e32 v177, s99
	v_mov_b32_e32 v176, s98
	v_sub_f32_e32 v178, v180, v177
	v_mul_f32_e32 v179, 0x3fb8aa3b, v178
	v_fma_f32 v180, v178, s46, -v179
	v_rndne_f32_e32 v181, v179
	v_fmac_f32_e32 v180, 0x32a5705f, v178
	v_sub_f32_e32 v179, v179, v181
	v_add_f32_e32 v179, v179, v180
	v_cvt_i32_f32_e32 v181, v181
	v_exp_f32_e32 v179, v179
	v_cmp_ngt_f32_e32 vcc, s47, v178
	v_ldexp_f32 v179, v179, v181
	s_nop 0
	v_cndmask_b32_e32 v179, 0, v179, vcc
	v_cmp_nlt_f32_e32 vcc, s62, v178
	s_nop 1
	v_cndmask_b32_e32 v178, v143, v179, vcc
	ds_write_b32 v65, v178 offset:36864
	s_and_saveexec_b64 vcc, s[16:17]
	s_cbranch_execz .LBB0_614
	s_lshl_b32 s94, s44, 8
	s_add_i32 s92, s94, s83
	s_ashr_i32 s93, s92, 31
	s_lshl_b64 s[92:93], s[92:93], 2
	s_add_u32 s100, s34, s92
	s_addc_u32 s101, s35, s93
	s_add_u32 s92, s36, s92
	s_addc_u32 s93, s37, s93
	global_store_dword v67, v176, s[100:101]
	global_store_dword v67, v177, s[92:93]
; __device__ __forceinline__ u32x4 pack8(const float (&v)[8]) { u32x4 o; o.x = pk2(v[0], v[1]); o.y = pk2(v[2], v[3]); o.z = pk2(v[4], v[5]); o.w = pk2(v[6], v[7]); return o; }
; __device__ __forceinline__ void conv4x8(const bf16* proj, int t, int ch, const float* cw, const float* cb, float sc, float (&o)[4][8]) {
;     ...
; #pragma unroll
;     for (int w = 0; w < 4; ++w) {
;         const f32x4 w0 = *(const f32x4*)(cw + w * 1024 + ch), w1 = *(const f32x4*)(cw + w * 1024 + ch + 4);
;         const float wv[8] = {w0[0], w0[1], w0[2], w0[3], w1[0], w1[1], w1[2], w1[3]};
; #pragma unroll
;         for (int j = 0; j < 4; ++j) { float xv[8]; unpack8(raw[j + w], xv);
; #pragma unroll
;             for (int e = 0; e < 8; ++e) o[j][e] += wv[e] * xv[e]; }
;     }
; #pragma unroll
;     for (int j = 0; j < 4; ++j)
; #pragma unroll
;         for (int e = 0; e < 8; ++e) o[j][e] = o[j][e] * sc * __builtin_amdgcn_rcpf(1.0f + __expf(-o[j][e]));
; }
; __device__ __forceinline__ void m1_phase(const Params& p, unsigned char* ldsg, int G) {
;     ...
;             conv4x8(PROJ, t0 + l0, h * HD + cgp * 8, p.convw, p.convb, 1.0f, qv);
; #pragma unroll
;             for (int j = 0; j < 4; ++j) *(u32x4*)(QKC + (size_t)(t0 + l0 + j) * DM + h * HD + cgp * 8) = pack8(qv[j]);
.LBB0_614:
	s_or_b64 exec, exec, vcc
.Lm1gate_skip:
	s_waitcnt vmcnt(19)
	v_mov_b32_e32 v88, v14
	s_waitcnt vmcnt(17)
	v_mov_b32_e32 v86, v18
	v_mov_b32_e32 v87, v20
	v_mov_b32_e32 v89, v16
	v_mov_b32_e32 v20, v19
	v_mov_b32_e32 v16, v15
	v_pk_fma_f32 v[104:105], v[86:87], v[98:99], v[88:89]
	v_pk_fma_f32 v[106:107], v[20:21], v[100:101], v[16:17]
	v_lshlrev_b32_e32 v99, 16, v55
	v_lshlrev_b32_e32 v98, 16, v54
	v_and_b32_e32 v101, 0xffff0000, v55
	v_and_b32_e32 v100, 0xffff0000, v54
	v_lshlrev_b32_e32 v15, 16, v59
	v_lshlrev_b32_e32 v14, 16, v58
	v_and_b32_e32 v19, 0xffff0000, v59
	v_and_b32_e32 v18, 0xffff0000, v58
	s_waitcnt vmcnt(16)
	v_mov_b32_e32 v54, v34
	v_mov_b32_e32 v55, v36
	v_pk_fma_f32 v[58:59], v[54:55], v[96:97], v[104:105]
	v_mov_b32_e32 v36, v35
	v_pk_fma_f32 v[104:105], v[36:37], v[94:95], v[106:107]
	s_waitcnt vmcnt(14)
	v_mov_b32_e32 v34, v38
	v_mov_b32_e32 v35, v40
	v_pk_fma_f32 v[58:59], v[34:35], v[98:99], v[58:59]
	v_mov_b32_e32 v40, v39
	s_waitcnt vmcnt(12)
	v_mov_b32_e32 v38, v46
	v_mov_b32_e32 v39, v48
	v_pk_fma_f32 v[58:59], v[38:39], v[14:15], v[58:59]
	v_pk_fma_f32 v[104:105], v[40:41], v[100:101], v[104:105]
	v_mul_f32_e32 v1, 0xbfb8aa3b, v58
	v_exp_f32_e32 v1, v1
	v_mov_b32_e32 v48, v47
	v_pk_fma_f32 v[46:47], v[48:49], v[18:19], v[104:105]
	v_pk_fma_f32 v[94:95], v[20:21], v[94:95], v[16:17]
	v_add_f32_e32 v1, 1.0, v1
	v_rcp_f32_e32 v104, v1
	v_mul_f32_e32 v1, 0xbfb8aa3b, v46
	v_exp_f32_e32 v1, v1
	v_pk_fma_f32 v[94:95], v[36:37], v[100:101], v[94:95]
	v_add_f32_e32 v1, 1.0, v1
	v_rcp_f32_e32 v108, v1
	v_mul_f32_e32 v1, 0xbfb8aa3b, v59
	v_exp_f32_e32 v1, v1
	v_pk_fma_f32 v[94:95], v[40:41], v[18:19], v[94:95]
	v_add_f32_e32 v1, 1.0, v1
	v_rcp_f32_e32 v105, v1
	v_mul_f32_e32 v1, 0xbfb8aa3b, v47
	v_exp_f32_e32 v1, v1
	v_pk_mul_f32 v[106:107], v[58:59], v[104:105]
	v_mov_b32_e32 v58, v6
	v_add_f32_e32 v1, 1.0, v1
	v_rcp_f32_e32 v109, v1
	v_mov_b32_e32 v59, v8
	v_and_b32_e32 v105, 0xffff0000, v57
	v_and_b32_e32 v104, 0xffff0000, v56
	v_pk_mul_f32 v[108:109], v[46:47], v[108:109]
	v_mov_b32_e32 v46, v10
	v_mov_b32_e32 v47, v12
	v_pk_fma_f32 v[114:115], v[46:47], v[102:103], v[58:59]
	v_lshlrev_b32_e32 v103, 16, v57
	v_lshlrev_b32_e32 v102, 16, v56
	v_mov_b32_e32 v56, v22
	v_mov_b32_e32 v57, v24
	v_mov_b32_e32 v12, v11
	v_mov_b32_e32 v8, v7
	v_lshlrev_b32_e32 v7, 16, v61
	v_lshlrev_b32_e32 v6, 16, v60
	v_and_b32_e32 v11, 0xffff0000, v61
	v_and_b32_e32 v10, 0xffff0000, v60
	v_pk_fma_f32 v[60:61], v[56:57], v[90:91], v[114:115]
	v_mov_b32_e32 v24, v23
	v_mov_b32_e32 v22, v26
	v_mov_b32_e32 v23, v28
	v_pk_fma_f32 v[60:61], v[22:23], v[102:103], v[60:61]
	v_mov_b32_e32 v28, v27
	s_waitcnt vmcnt(11)
	v_mov_b32_e32 v26, v42
	v_mov_b32_e32 v27, v44
	v_pk_fma_f32 v[60:61], v[26:27], v[6:7], v[60:61]
	v_pk_fma_f32 v[82:83], v[12:13], v[82:83], v[8:9]
	v_mul_f32_e32 v1, 0xbfb8aa3b, v60
	v_exp_f32_e32 v1, v1
	v_pk_fma_f32 v[82:83], v[24:25], v[84:85], v[82:83]
	v_mov_b32_e32 v44, v43
	v_pk_fma_f32 v[82:83], v[28:29], v[104:105], v[82:83]
	v_add_f32_e32 v1, 1.0, v1
	v_pk_fma_f32 v[42:43], v[44:45], v[10:11], v[82:83]
	v_rcp_f32_e32 v82, v1
	v_mul_f32_e32 v1, 0xbfb8aa3b, v42
	v_exp_f32_e32 v1, v1
	v_bfe_u32 v77, v109, 16, 1
	v_add3_u32 v77, v109, v77, s81
	v_bfe_u32 v79, v108, 16, 1
	v_add_f32_e32 v1, 1.0, v1
	v_rcp_f32_e32 v114, v1
	v_mul_f32_e32 v1, 0xbfb8aa3b, v61
	v_exp_f32_e32 v1, v1
	v_add3_u32 v79, v108, v79, s81
	v_pk_fma_f32 v[90:91], v[46:47], v[90:91], v[58:59]
	v_pk_fma_f32 v[84:85], v[12:13], v[84:85], v[8:9]
	v_add_f32_e32 v1, 1.0, v1
	v_rcp_f32_e32 v83, v1
	v_mul_f32_e32 v1, 0xbfb8aa3b, v43
	v_exp_f32_e32 v1, v1
	v_pk_fma_f32 v[90:91], v[56:57], v[102:103], v[90:91]
	v_pk_mul_f32 v[60:61], v[60:61], v[82:83]
	v_pk_fma_f32 v[90:91], v[22:23], v[6:7], v[90:91]
	v_add_f32_e32 v1, 1.0, v1
	v_rcp_f32_e32 v115, v1
	v_bfe_u32 v81, v60, 16, 1
	v_bfe_u32 v82, v61, 16, 1
	v_add3_u32 v61, v61, v82, s81
	v_pk_mul_f32 v[42:43], v[42:43], v[114:115]
	v_add3_u32 v60, v60, v81, s81
	v_bfe_u32 v75, v42, 16, 1
	v_add3_u32 v42, v42, v75, s81
	v_bfe_u32 v75, v107, 16, 1
	v_bfe_u32 v1, v43, 16, 1
	v_add3_u32 v75, v107, v75, s81
	v_add3_u32 v1, v43, v1, s81
	v_bfe_u32 v43, v106, 16, 1
	v_lshrrev_b32_e32 v75, 16, v75
	v_add3_u32 v43, v106, v43, s81
	v_and_or_b32 v107, v77, s64, v75
	v_ashrrev_i32_e32 v75, 31, v74
	v_lshrrev_b32_e32 v43, 16, v43
	v_lshrrev_b32_e32 v60, 16, v60
	v_lshrrev_b32_e32 v61, 16, v61
	v_lshlrev_b64 v[82:83], 11, v[74:75]
	v_and_or_b32 v109, v1, s64, v61
	v_and_or_b32 v108, v42, s64, v60
	v_and_or_b32 v106, v79, s64, v43
	v_lshl_add_u64 v[42:43], v[62:63], 0, v[82:83]
	global_store_dwordx4 v[42:43], v[106:109], off
	v_pk_fma_f32 v[42:43], v[86:87], v[96:97], v[88:89]
	v_lshlrev_b32_e32 v61, 16, v51
	v_pk_fma_f32 v[42:43], v[54:55], v[98:99], v[42:43]
	v_lshlrev_b32_e32 v60, 16, v50
	v_pk_fma_f32 v[42:43], v[34:35], v[14:15], v[42:43]
	v_and_b32_e32 v51, 0xffff0000, v51
	v_pk_fma_f32 v[42:43], v[38:39], v[60:61], v[42:43]
	v_and_b32_e32 v50, 0xffff0000, v50
	v_mul_f32_e32 v1, 0xbfb8aa3b, v42
	v_exp_f32_e32 v1, v1
	v_pk_fma_f32 v[94:95], v[48:49], v[50:51], v[94:95]
	v_pk_fma_f32 v[84:85], v[24:25], v[104:105], v[84:85]
	v_add_f32_e32 v1, 1.0, v1
	v_rcp_f32_e32 v96, v1
	v_mul_f32_e32 v1, 0xbfb8aa3b, v94
	v_exp_f32_e32 v1, v1
	v_pk_fma_f32 v[84:85], v[28:29], v[10:11], v[84:85]
	v_add_f32_e32 v1, 1.0, v1
	v_rcp_f32_e32 v106, v1
	v_mul_f32_e32 v1, 0xbfb8aa3b, v43
	v_exp_f32_e32 v1, v1
	s_nop 0
	v_add_f32_e32 v1, 1.0, v1
	v_rcp_f32_e32 v97, v1
	v_mul_f32_e32 v1, 0xbfb8aa3b, v95
	v_exp_f32_e32 v1, v1
	v_pk_mul_f32 v[96:97], v[42:43], v[96:97]
	v_lshlrev_b32_e32 v43, 16, v53
	v_lshlrev_b32_e32 v42, 16, v52
; __device__ __forceinline__ unsigned pk2(float lo, float hi) { return f2bf(lo) | (f2bf(hi) << 16); }
; __device__ __forceinline__ void conv4x8(const bf16* proj, int t, int ch, const float* cw, const float* cb, float sc, float (&o)[4][8]) {
;     ...
;         for (int j = 0; j < 4; ++j) { float xv[8]; unpack8(raw[j + w], xv);
; #pragma unroll
;             for (int e = 0; e < 8; ++e) o[j][e] += wv[e] * xv[e]; }
;     }
; #pragma unroll
;     for (int j = 0; j < 4; ++j)
; #pragma unroll
;         for (int e = 0; e < 8; ++e) o[j][e] = o[j][e] * sc * __builtin_amdgcn_rcpf(1.0f + __expf(-o[j][e]));
; }
; __device__ __forceinline__ u32x4 pack8(const float (&v)[8]) { u32x4 o; o.x = pk2(v[0], v[1]); o.y = pk2(v[2], v[3]); o.z = pk2(v[4], v[5]); o.w = pk2(v[6], v[7]); return o; }
; __device__ __forceinline__ void m1_phase(const Params& p, unsigned char* ldsg, int G) {
;     ...
;             conv4x8(PROJ, t0 + l0, h * HD + cgp * 8, p.convw, p.convb, 1.0f, qv);
; #pragma unroll
;             for (int j = 0; j < 4; ++j) *(u32x4*)(QKC + (size_t)(t0 + l0 + j) * DM + h * HD + cgp * 8) = pack8(qv[j]);
	v_add_f32_e32 v1, 1.0, v1
	v_pk_fma_f32 v[90:91], v[26:27], v[42:43], v[90:91]
	v_rcp_f32_e32 v107, v1
	v_mul_f32_e32 v1, 0xbfb8aa3b, v90
	v_exp_f32_e32 v1, v1
	v_and_b32_e32 v53, 0xffff0000, v53
	v_and_b32_e32 v52, 0xffff0000, v52
	v_pk_fma_f32 v[84:85], v[44:45], v[52:53], v[84:85]
	v_add_f32_e32 v1, 1.0, v1
	v_pk_mul_f32 v[94:95], v[94:95], v[106:107]
	v_rcp_f32_e32 v106, v1
	v_mul_f32_e32 v1, 0xbfb8aa3b, v84
	v_exp_f32_e32 v1, v1
	v_bfe_u32 v77, v95, 16, 1
	v_bfe_u32 v79, v94, 16, 1
	v_add3_u32 v79, v94, v79, s81
	v_add_f32_e32 v1, 1.0, v1
	v_rcp_f32_e32 v108, v1
	v_mul_f32_e32 v1, 0xbfb8aa3b, v91
	v_exp_f32_e32 v1, v1
	v_add3_u32 v77, v95, v77, s81
	v_bfe_u32 v81, v96, 16, 1
	v_add3_u32 v81, v96, v81, s81
	v_add_f32_e32 v1, 1.0, v1
	v_rcp_f32_e32 v107, v1
	v_mul_f32_e32 v1, 0xbfb8aa3b, v85
	v_exp_f32_e32 v1, v1
	v_lshrrev_b32_e32 v81, 16, v81
	v_pk_mul_f32 v[90:91], v[90:91], v[106:107]
	v_add_f32_e32 v1, 1.0, v1
	v_rcp_f32_e32 v109, v1
	v_bfe_u32 v94, v91, 16, 1
	v_add3_u32 v91, v91, v94, s81
	v_and_or_b32 v94, v79, s64, v81
	v_pk_mul_f32 v[84:85], v[84:85], v[108:109]
	s_nop 0
	v_bfe_u32 v75, v84, 16, 1
	v_bfe_u32 v1, v85, 16, 1
	v_add3_u32 v75, v84, v75, s81
	v_bfe_u32 v84, v97, 16, 1
	v_add3_u32 v1, v85, v1, s81
	v_bfe_u32 v85, v90, 16, 1
	v_add3_u32 v84, v97, v84, s81
	v_add3_u32 v85, v90, v85, s81
	v_lshrrev_b32_e32 v84, 16, v84
	v_lshrrev_b32_e32 v85, 16, v85
	v_and_or_b32 v95, v77, s64, v84
	v_ashrrev_i32_e32 v77, 31, v76
	v_lshrrev_b32_e32 v90, 16, v91
	v_and_or_b32 v96, v75, s64, v85
	v_lshlrev_b64 v[84:85], 11, v[76:77]
	v_and_or_b32 v97, v1, s64, v90
	v_lshl_add_u64 v[90:91], v[62:63], 0, v[84:85]
	global_store_dwordx4 v[90:91], v[94:97], off
	v_pk_fma_f32 v[90:91], v[20:21], v[100:101], v[16:17]
	v_pk_fma_f32 v[16:17], v[20:21], v[18:19], v[16:17]
	v_lshlrev_b32_e32 v95, 16, v31
	v_lshlrev_b32_e32 v94, 16, v30
	v_and_b32_e32 v97, 0xffff0000, v31
	v_and_b32_e32 v96, 0xffff0000, v30
	v_pk_fma_f32 v[30:31], v[86:87], v[98:99], v[88:89]
	v_pk_fma_f32 v[90:91], v[36:37], v[18:19], v[90:91]
	v_pk_fma_f32 v[30:31], v[54:55], v[14:15], v[30:31]
	v_pk_fma_f32 v[90:91], v[40:41], v[50:51], v[90:91]
	v_pk_fma_f32 v[30:31], v[34:35], v[60:61], v[30:31]
	v_pk_fma_f32 v[90:91], v[48:49], v[96:97], v[90:91]
	v_pk_fma_f32 v[30:31], v[38:39], v[94:95], v[30:31]
	v_pk_fma_f32 v[14:15], v[86:87], v[14:15], v[88:89]
	v_mul_f32_e32 v1, 0xbfb8aa3b, v30
	v_exp_f32_e32 v1, v1
	v_pk_fma_f32 v[14:15], v[54:55], v[60:61], v[14:15]
	v_pk_fma_f32 v[16:17], v[36:37], v[50:51], v[16:17]
	v_pk_fma_f32 v[14:15], v[34:35], v[94:95], v[14:15]
	v_add_f32_e32 v1, 1.0, v1
	v_rcp_f32_e32 v98, v1
	v_mul_f32_e32 v1, 0xbfb8aa3b, v90
	v_exp_f32_e32 v1, v1
	v_pk_fma_f32 v[16:17], v[40:41], v[96:97], v[16:17]
	v_add_f32_e32 v1, 1.0, v1
	v_rcp_f32_e32 v100, v1
	v_mul_f32_e32 v1, 0xbfb8aa3b, v31
	v_exp_f32_e32 v1, v1
	s_nop 0
	v_add_f32_e32 v1, 1.0, v1
	v_rcp_f32_e32 v99, v1
	v_mul_f32_e32 v1, 0xbfb8aa3b, v91
	v_exp_f32_e32 v1, v1
	v_pk_mul_f32 v[30:31], v[30:31], v[98:99]
	v_lshlrev_b32_e32 v99, 16, v33
	v_add_f32_e32 v1, 1.0, v1
	v_rcp_f32_e32 v101, v1
	v_lshlrev_b32_e32 v98, 16, v32
	v_bfe_u32 v81, v30, 16, 1
	v_add3_u32 v30, v30, v81, s81
	v_pk_mul_f32 v[90:91], v[90:91], v[100:101]
	v_and_b32_e32 v101, 0xffff0000, v33
	v_and_b32_e32 v100, 0xffff0000, v32
	v_pk_fma_f32 v[32:33], v[46:47], v[102:103], v[58:59]
	v_pk_fma_f32 v[102:103], v[12:13], v[104:105], v[8:9]
	v_pk_fma_f32 v[32:33], v[56:57], v[6:7], v[32:33]
	v_pk_fma_f32 v[102:103], v[24:25], v[10:11], v[102:103]
	v_pk_fma_f32 v[32:33], v[22:23], v[42:43], v[32:33]
	v_pk_fma_f32 v[102:103], v[28:29], v[52:53], v[102:103]
	v_pk_fma_f32 v[32:33], v[26:27], v[98:99], v[32:33]
	v_pk_fma_f32 v[102:103], v[44:45], v[100:101], v[102:103]
	v_mul_f32_e32 v1, 0xbfb8aa3b, v32
	v_exp_f32_e32 v1, v1
	v_bfe_u32 v77, v91, 16, 1
	v_bfe_u32 v79, v90, 16, 1
	v_add3_u32 v79, v90, v79, s81
	v_add_f32_e32 v1, 1.0, v1
	v_rcp_f32_e32 v104, v1
	v_mul_f32_e32 v1, 0xbfb8aa3b, v102
	v_exp_f32_e32 v1, v1
	v_add3_u32 v77, v91, v77, s81
	v_bfe_u32 v90, v31, 16, 1
	v_lshrrev_b32_e32 v30, 16, v30
	v_add_f32_e32 v1, 1.0, v1
	v_rcp_f32_e32 v106, v1
	v_mul_f32_e32 v1, 0xbfb8aa3b, v33
	v_exp_f32_e32 v1, v1
	v_add3_u32 v31, v31, v90, s81
	v_and_or_b32 v30, v79, s64, v30
	v_ashrrev_i32_e32 v79, 31, v78
	v_add_f32_e32 v1, 1.0, v1
	v_rcp_f32_e32 v105, v1
	v_mul_f32_e32 v1, 0xbfb8aa3b, v103
	v_exp_f32_e32 v1, v1
	v_lshrrev_b32_e32 v31, 16, v31
	v_pk_mul_f32 v[32:33], v[32:33], v[104:105]
	v_and_or_b32 v31, v77, s64, v31
	v_add_f32_e32 v1, 1.0, v1
	v_rcp_f32_e32 v107, v1
	v_bfe_u32 v91, v32, 16, 1
	v_add3_u32 v32, v32, v91, s81
	v_lshrrev_b32_e32 v32, 16, v32
	v_pk_mul_f32 v[102:103], v[102:103], v[106:107]
	v_lshlrev_b64 v[90:91], 11, v[78:79]
	v_bfe_u32 v75, v102, 16, 1
	v_add3_u32 v75, v102, v75, s81
	v_bfe_u32 v102, v33, 16, 1
	v_bfe_u32 v1, v103, 16, 1
	v_add3_u32 v33, v33, v102, s81
	v_add3_u32 v1, v103, v1, s81
	v_lshrrev_b32_e32 v33, 16, v33
	v_and_or_b32 v33, v1, s64, v33
	v_and_or_b32 v32, v75, s64, v32
	v_lshl_add_u64 v[102:103], v[62:63], 0, v[90:91]
	global_store_dwordx4 v[102:103], v[30:33], off
	v_pk_fma_f32 v[6:7], v[46:47], v[6:7], v[58:59]
	v_pk_fma_f32 v[8:9], v[12:13], v[10:11], v[8:9]
	v_lshlrev_b32_e32 v31, 16, v3
	v_lshlrev_b32_e32 v30, 16, v2
	v_pk_fma_f32 v[14:15], v[38:39], v[30:31], v[14:15]
	v_and_b32_e32 v3, 0xffff0000, v3
	v_mul_f32_e32 v1, 0xbfb8aa3b, v14
	v_exp_f32_e32 v1, v1
	v_and_b32_e32 v2, 0xffff0000, v2
	v_pk_fma_f32 v[2:3], v[48:49], v[2:3], v[16:17]
	v_pk_fma_f32 v[6:7], v[56:57], v[42:43], v[6:7]
	v_add_f32_e32 v1, 1.0, v1
	v_rcp_f32_e32 v16, v1
	v_mul_f32_e32 v1, 0xbfb8aa3b, v2
	v_exp_f32_e32 v1, v1
; __device__ __forceinline__ u32x4 pack8(const float (&v)[8]) { u32x4 o; o.x = pk2(v[0], v[1]); o.y = pk2(v[2], v[3]); o.z = pk2(v[4], v[5]); o.w = pk2(v[6], v[7]); return o; }
; __device__ __forceinline__ void conv4x8(const bf16* proj, int t, int ch, const float* cw, const float* cb, float sc, float (&o)[4][8]) {
;     u32x4 raw[7];
; #pragma unroll
;     for (int i = 0; i < 7; ++i) { const int tr = t - 3 + i; raw[i] = tr >= 0 ? *(const u32x4*)(proj + (size_t)tr * NPROJ + ch) : (u32x4){0u, 0u, 0u, 0u}; }
;     { const f32x4 b0 = *(const f32x4*)(cb + ch), b1 = *(const f32x4*)(cb + ch + 4);
; #pragma unroll
;       for (int j = 0; j < 4; ++j) { o[j][0] = b0[0]; o[j][1] = b0[1]; o[j][2] = b0[2]; o[j][3] = b0[3]; o[j][4] = b1[0]; o[j][5] = b1[1]; o[j][6] = b1[2]; o[j][7] = b1[3]; } }
; #pragma unroll
;     for (int w = 0; w < 4; ++w) {
;         const f32x4 w0 = *(const f32x4*)(cw + w * 1024 + ch), w1 = *(const f32x4*)(cw + w * 1024 + ch + 4);
;         const float wv[8] = {w0[0], w0[1], w0[2], w0[3], w1[0], w1[1], w1[2], w1[3]};
; #pragma unroll
;         for (int j = 0; j < 4; ++j) { float xv[8]; unpack8(raw[j + w], xv);
; #pragma unroll
;             for (int e = 0; e < 8; ++e) o[j][e] += wv[e] * xv[e]; }
;     }
; __device__ __forceinline__ void m1_phase(const Params& p, unsigned char* ldsg, int G) {
;     ...
;             conv4x8(PROJ, t0 + l0, h * HD + cgp * 8, p.convw, p.convb, 1.0f, qv);
; #pragma unroll
;             for (int j = 0; j < 4; ++j) *(u32x4*)(QKC + (size_t)(t0 + l0 + j) * DM + h * HD + cgp * 8) = pack8(qv[j]);
;         }
;         asm volatile("" ::: "memory");
;         conv4x8(PROJ, t0 + l0, 512 + h * HD + cgp * 8, p.convw, p.convb, 0.08838834764831845f, kk);
; #pragma unroll
;         for (int j = 0; j < 4; ++j) *(u32x4*)(QKC + (size_t)(t0 + l0 + j) * DM + 512 + h * HD + cgp * 8) = pack8(kk[j]);
	v_pk_fma_f32 v[6:7], v[22:23], v[98:99], v[6:7]
	v_pk_fma_f32 v[8:9], v[24:25], v[52:53], v[8:9]
	v_ashrrev_i32_e32 v81, 31, v80
	v_add_f32_e32 v1, 1.0, v1
	v_rcp_f32_e32 v18, v1
	v_mul_f32_e32 v1, 0xbfb8aa3b, v15
	v_exp_f32_e32 v1, v1
	v_pk_fma_f32 v[8:9], v[28:29], v[100:101], v[8:9]
	v_lshlrev_b64 v[86:87], 11, v[80:81]
	v_add_f32_e32 v1, 1.0, v1
	v_rcp_f32_e32 v17, v1
	v_mul_f32_e32 v1, 0xbfb8aa3b, v3
	v_exp_f32_e32 v1, v1
	v_pk_mul_f32 v[14:15], v[14:15], v[16:17]
	v_lshlrev_b32_e32 v17, 16, v5
	v_lshlrev_b32_e32 v16, 16, v4
	v_add_f32_e32 v1, 1.0, v1
	v_pk_fma_f32 v[6:7], v[26:27], v[16:17], v[6:7]
	v_rcp_f32_e32 v19, v1
	v_mul_f32_e32 v1, 0xbfb8aa3b, v6
	v_exp_f32_e32 v1, v1
	v_and_b32_e32 v5, 0xffff0000, v5
	v_and_b32_e32 v4, 0xffff0000, v4
	v_pk_fma_f32 v[4:5], v[44:45], v[4:5], v[8:9]
	v_add_f32_e32 v1, 1.0, v1
	v_rcp_f32_e32 v8, v1
	v_mul_f32_e32 v1, 0xbfb8aa3b, v4
	v_exp_f32_e32 v1, v1
	v_pk_mul_f32 v[2:3], v[2:3], v[18:19]
	v_add_f32_e32 v1, 1.0, v1
	v_rcp_f32_e32 v10, v1
	v_mul_f32_e32 v1, 0xbfb8aa3b, v7
	v_exp_f32_e32 v1, v1
	s_nop 0
	v_add_f32_e32 v1, 1.0, v1
	v_rcp_f32_e32 v9, v1
	v_mul_f32_e32 v1, 0xbfb8aa3b, v5
	v_exp_f32_e32 v1, v1
	v_pk_mul_f32 v[6:7], v[6:7], v[8:9]
	v_bfe_u32 v9, v3, 16, 1
	v_add_f32_e32 v1, 1.0, v1
	v_rcp_f32_e32 v11, v1
	v_add3_u32 v3, v3, v9, s81
	v_bfe_u32 v9, v6, 16, 1
	v_add3_u32 v6, v6, v9, s81
	v_pk_mul_f32 v[4:5], v[4:5], v[10:11]
	v_bfe_u32 v10, v2, 16, 1
	v_bfe_u32 v1, v5, 16, 1
	v_bfe_u32 v8, v4, 16, 1
	v_add3_u32 v2, v2, v10, s81
	v_add3_u32 v4, v4, v8, s81
	v_add3_u32 v1, v5, v1, s81
	v_bfe_u32 v5, v14, 16, 1
	v_bfe_u32 v8, v15, 16, 1
	v_bfe_u32 v10, v7, 16, 1
	v_add3_u32 v7, v7, v10, s81
	v_add3_u32 v8, v15, v8, s81
	v_add3_u32 v5, v14, v5, s81
	v_lshrrev_b32_e32 v9, 16, v5
	v_lshrrev_b32_e32 v8, 16, v8
	v_lshrrev_b32_e32 v6, 16, v6
	v_lshrrev_b32_e32 v5, 16, v7
	v_and_or_b32 v5, v1, s64, v5
	v_and_or_b32 v4, v4, s64, v6
	v_and_or_b32 v3, v3, s64, v8
	v_and_or_b32 v2, v2, s64, v9
	v_lshl_add_u64 v[6:7], v[62:63], 0, v[86:87]
	global_store_dwordx4 v[6:7], v[2:5], off
	v_add_u32_e32 v8, s58, v119
	v_ashrrev_i32_e32 v9, 31, v8
	v_lshlrev_b64 v[12:13], 2, v[8:9]
	v_lshl_add_u64 v[32:33], s[48:49], 0, v[12:13]
	v_add_co_u32_e32 v28, vcc, s65, v32
	v_lshl_add_u64 v[12:13], s[50:51], 0, v[12:13]
	s_nop 0
	v_addc_co_u32_e32 v29, vcc, 0, v33, vcc
	global_load_dwordx4 v[16:19], v[32:33], off
	global_load_dwordx4 v[8:11], v[32:33], off offset:16
	global_load_dwordx4 v[20:23], v[12:13], off
	s_nop 0
	global_load_dwordx4 v[12:15], v[12:13], off offset:16
	s_nop 0
	global_load_dwordx4 v[36:39], v[28:29], off offset:-4096
	global_load_dwordx4 v[40:43], v[28:29], off
	v_add_co_u32_e32 v28, vcc, s80, v32
	s_waitcnt vmcnt(6)
	v_lshlrev_b32_e32 v95, 16, v189
	v_addc_co_u32_e32 v29, vcc, 0, v33, vcc
	global_load_dwordx4 v[44:47], v[28:29], off
	v_lshlrev_b32_e32 v94, 16, v188
	v_and_b32_e32 v97, 0xffff0000, v189
	v_and_b32_e32 v96, 0xffff0000, v188
	v_lshl_add_u64 v[0:1], v[32:33], 0, s[6:7]
	global_load_dwordx4 v[28:31], v[0:1], off offset:16
	v_lshl_add_u64 v[0:1], v[32:33], 0, s[38:39]
	v_lshlrev_b32_e32 v101, 16, v191
	v_lshlrev_b32_e32 v100, 16, v190
	v_and_b32_e32 v107, 0xffff0000, v191
	v_and_b32_e32 v106, 0xffff0000, v190
	global_load_dwordx4 v[0:3], v[0:1], off offset:16
	v_lshl_add_u64 v[32:33], v[32:33], 0, s[40:41]
	global_load_dwordx4 v[32:35], v[32:33], off offset:16
	v_lshlrev_b32_e32 v117, 16, v193
	v_lshlrev_b32_e32 v116, 16, v192
	v_and_b32_e32 v177, 0xffff0000, v193
	v_and_b32_e32 v176, 0xffff0000, v192
	v_lshlrev_b32_e32 v113, 16, v195
	v_lshlrev_b32_e32 v112, 16, v194
	v_and_b32_e32 v115, 0xffff0000, v195
	v_and_b32_e32 v114, 0xffff0000, v194
	v_lshlrev_b32_e32 v110, 16, v196
	v_and_b32_e32 v108, 0xffff0000, v196
	v_lshlrev_b32_e32 v111, 16, v197
	v_and_b32_e32 v109, 0xffff0000, v197
	v_lshlrev_b32_e32 v104, 16, v198
	v_and_b32_e32 v102, 0xffff0000, v198
	v_lshlrev_b32_e32 v105, 16, v199
	v_and_b32_e32 v103, 0xffff0000, v199
	v_lshlrev_b32_e32 v57, 16, v201
	v_lshlrev_b32_e32 v56, 16, v200
	v_and_b32_e32 v59, 0xffff0000, v201
	v_and_b32_e32 v58, 0xffff0000, v200
	s_lshl_b64 s[0:1], s[58:59], 1
	v_lshl_add_u64 v[84:85], s[56:57], 0, v[84:85]
	v_lshl_add_u64 v[84:85], v[84:85], 0, s[0:1]
	v_lshl_add_u64 v[84:85], v[84:85], 0, v[66:67]
	v_lshl_add_u64 v[90:91], s[56:57], 0, v[90:91]
	v_lshl_add_u64 v[90:91], v[90:91], 0, s[0:1]
	v_lshl_add_u64 v[90:91], v[90:91], 0, v[66:67]
	s_waitcnt vmcnt(9)
	v_mov_b32_e32 v60, v16
	v_mov_b32_e32 v61, v18
	v_mov_b32_e32 v18, v17
	s_waitcnt vmcnt(7)
	v_mov_b32_e32 v62, v20
	v_mov_b32_e32 v63, v22
	v_mov_b32_e32 v22, v21
	v_mov_b32_e32 v52, v8
	v_mov_b32_e32 v53, v10
	v_mov_b32_e32 v10, v9
	v_pk_fma_f32 v[8:9], v[60:61], v[94:95], v[62:63]
	v_pk_fma_f32 v[16:17], v[18:19], v[96:97], v[22:23]
	s_waitcnt vmcnt(5)
	v_mov_b32_e32 v94, v36
	v_mov_b32_e32 v95, v38
	v_mov_b32_e32 v38, v37
	s_waitcnt vmcnt(4)
	v_mov_b32_e32 v96, v40
	v_mov_b32_e32 v97, v42
	v_mov_b32_e32 v42, v41
	v_pk_fma_f32 v[8:9], v[94:95], v[116:117], v[8:9]
	v_pk_fma_f32 v[16:17], v[38:39], v[176:177], v[16:17]
	s_waitcnt vmcnt(3)
; __device__ __forceinline__ unsigned pk2(float lo, float hi) { return f2bf(lo) | (f2bf(hi) << 16); }
; __device__ __forceinline__ void conv4x8(const bf16* proj, int t, int ch, const float* cw, const float* cb, float sc, float (&o)[4][8]) {
;     ...
;     for (int w = 0; w < 4; ++w) {
;         const f32x4 w0 = *(const f32x4*)(cw + w * 1024 + ch), w1 = *(const f32x4*)(cw + w * 1024 + ch + 4);
;         const float wv[8] = {w0[0], w0[1], w0[2], w0[3], w1[0], w1[1], w1[2], w1[3]};
; #pragma unroll
;         for (int j = 0; j < 4; ++j) { float xv[8]; unpack8(raw[j + w], xv);
; #pragma unroll
;             for (int e = 0; e < 8; ++e) o[j][e] += wv[e] * xv[e]; }
;     }
; #pragma unroll
;     for (int j = 0; j < 4; ++j)
; #pragma unroll
;         for (int e = 0; e < 8; ++e) o[j][e] = o[j][e] * sc * __builtin_amdgcn_rcpf(1.0f + __expf(-o[j][e]));
; }
; __device__ __forceinline__ u32x4 pack8(const float (&v)[8]) { u32x4 o; o.x = pk2(v[0], v[1]); o.y = pk2(v[2], v[3]); o.z = pk2(v[4], v[5]); o.w = pk2(v[6], v[7]); return o; }
; __device__ __forceinline__ void m1_phase(const Params& p, unsigned char* ldsg, int G) {
;     ...
;         conv4x8(PROJ, t0 + l0, 512 + h * HD + cgp * 8, p.convw, p.convb, 0.08838834764831845f, kk);
; #pragma unroll
;         for (int j = 0; j < 4; ++j) *(u32x4*)(QKC + (size_t)(t0 + l0 + j) * DM + 512 + h * HD + cgp * 8) = pack8(kk[j]);
	v_mov_b32_e32 v98, v44
	v_mov_b32_e32 v99, v46
	v_mov_b32_e32 v46, v45
	v_pk_fma_f32 v[8:9], v[96:97], v[110:111], v[8:9]
	v_pk_fma_f32 v[16:17], v[42:43], v[108:109], v[16:17]
	v_pk_fma_f32 v[8:9], v[98:99], v[56:57], v[8:9]
	v_pk_fma_f32 v[16:17], v[46:47], v[58:59], v[16:17]
	v_mov_b32_e32 v88, v12
	v_mul_f32_e32 v12, 0xbfb8aa3b, v8
	v_mul_f32_e32 v36, 0xbfb8aa3b, v16
	v_mul_f32_e32 v37, 0xbfb8aa3b, v9
	v_pk_mul_f32 v[20:21], v[8:9], s[42:43] op_sel_hi:[1,0]
	v_pk_mul_f32 v[8:9], v[16:17], s[42:43] op_sel_hi:[1,0]
	v_mul_f32_e32 v16, 0xbfb8aa3b, v17
	v_exp_f32_e32 v12, v12
	v_exp_f32_e32 v17, v36
	v_exp_f32_e32 v36, v37
	v_exp_f32_e32 v37, v16
	v_add_f32_e32 v12, 1.0, v12
	v_add_f32_e32 v40, 1.0, v17
	v_add_f32_e32 v17, 1.0, v36
	v_rcp_f32_e32 v16, v12
	v_rcp_f32_e32 v17, v17
	v_mov_b32_e32 v89, v14
	v_add_f32_e32 v12, 1.0, v37
	v_rcp_f32_e32 v36, v40
	v_pk_mul_f32 v[16:17], v[20:21], v[16:17]
	v_pk_fma_f32 v[20:21], v[52:53], v[100:101], v[88:89]
	v_mov_b32_e32 v14, v13
	v_lshlrev_b32_e32 v41, 16, v203
	v_lshlrev_b32_e32 v40, 16, v202
	v_and_b32_e32 v45, 0xffff0000, v203
	v_and_b32_e32 v44, 0xffff0000, v202
	s_waitcnt vmcnt(2)
	v_mov_b32_e32 v54, v28
	v_mov_b32_e32 v55, v30
	v_rcp_f32_e32 v37, v12
	v_pk_fma_f32 v[12:13], v[10:11], v[106:107], v[14:15]
	v_pk_fma_f32 v[20:21], v[54:55], v[112:113], v[20:21]
	v_mov_b32_e32 v30, v29
	s_waitcnt vmcnt(1)
	v_mov_b32_e32 v100, v0
	v_mov_b32_e32 v101, v2
	v_pk_fma_f32 v[12:13], v[30:31], v[114:115], v[12:13]
	v_pk_fma_f32 v[20:21], v[100:101], v[104:105], v[20:21]
	v_mov_b32_e32 v2, v1
	s_waitcnt vmcnt(0)
	v_mov_b32_e32 v106, v32
	v_mov_b32_e32 v107, v34
	v_pk_fma_f32 v[0:1], v[2:3], v[102:103], v[12:13]
	v_pk_fma_f32 v[20:21], v[106:107], v[40:41], v[20:21]
	v_mov_b32_e32 v34, v33
	v_pk_fma_f32 v[0:1], v[34:35], v[44:45], v[0:1]
	v_mul_f32_e32 v12, 0xbfb8aa3b, v20
	v_exp_f32_e32 v28, v12
	v_mul_f32_e32 v12, 0xbfb8aa3b, v0
	v_exp_f32_e32 v29, v12
	v_pk_mul_f32 v[12:13], v[8:9], v[36:37]
	v_add_f32_e32 v8, 1.0, v28
	v_mul_f32_e32 v28, 0xbfb8aa3b, v21
	v_add_f32_e32 v9, 1.0, v29
	v_exp_f32_e32 v29, v28
	v_mul_f32_e32 v28, 0xbfb8aa3b, v1
	v_exp_f32_e32 v32, v28
	v_rcp_f32_e32 v28, v9
	v_add_f32_e32 v9, 1.0, v29
	v_rcp_f32_e32 v8, v8
	v_rcp_f32_e32 v9, v9
	v_add_f32_e32 v29, 1.0, v32
	v_rcp_f32_e32 v29, v29
	v_pk_mul_f32 v[20:21], v[20:21], s[42:43] op_sel_hi:[1,0]
	v_pk_mul_f32 v[0:1], v[0:1], s[42:43] op_sel_hi:[1,0]
	v_pk_mul_f32 v[8:9], v[20:21], v[8:9]
	v_pk_mul_f32 v[0:1], v[0:1], v[28:29]
	v_bfe_u32 v36, v8, 16, 1
	v_bfe_u32 v37, v9, 16, 1
	v_bfe_u32 v20, v1, 16, 1
	v_bfe_u32 v21, v0, 16, 1
	v_add3_u32 v37, v9, v37, s81
	v_add3_u32 v36, v8, v36, s81
	v_add3_u32 v21, v0, v21, s81
	v_add3_u32 v20, v1, v20, s81
	v_bfe_u32 v32, v16, 16, 1
	v_bfe_u32 v33, v17, 16, 1
	v_lshrrev_b32_e32 v36, 16, v36
	v_lshrrev_b32_e32 v37, 16, v37
	v_bfe_u32 v28, v13, 16, 1
	v_bfe_u32 v29, v12, 16, 1
	v_add3_u32 v33, v17, v33, s81
	v_add3_u32 v32, v16, v32, s81
	v_and_or_b32 v151, v20, s64, v37
	v_and_or_b32 v150, v21, s64, v36
	v_lshl_add_u64 v[20:21], s[56:57], 0, v[82:83]
	v_add3_u32 v29, v12, v29, s81
	v_add3_u32 v28, v13, v28, s81
	v_lshrrev_b32_e32 v32, 16, v32
	v_lshrrev_b32_e32 v33, 16, v33
	v_lshl_add_u64 v[20:21], v[20:21], 0, s[0:1]
	v_and_or_b32 v149, v28, s64, v33
	v_and_or_b32 v148, v29, s64, v32
	v_lshl_add_u64 v[20:21], v[20:21], 0, v[66:67]
	v_pk_fma_f32 v[28:29], v[18:19], v[176:177], v[22:23]
	global_store_dwordx4 v[20:21], v[148:151], off offset:1024
	v_pk_fma_f32 v[20:21], v[60:61], v[116:117], v[62:63]
	v_pk_fma_f32 v[28:29], v[38:39], v[108:109], v[28:29]
	v_and_b32_e32 v83, 0xffff0000, v205
	v_and_b32_e32 v82, 0xffff0000, v204
	v_pk_fma_f32 v[20:21], v[94:95], v[110:111], v[20:21]
	v_pk_fma_f32 v[28:29], v[42:43], v[58:59], v[28:29]
	v_lshlrev_b32_e32 v117, 16, v205
	v_lshlrev_b32_e32 v116, 16, v204
	v_pk_fma_f32 v[20:21], v[96:97], v[56:57], v[20:21]
	v_pk_fma_f32 v[28:29], v[46:47], v[82:83], v[28:29]
	v_pk_fma_f32 v[20:21], v[98:99], v[116:117], v[20:21]
	v_mul_f32_e32 v33, 0xbfb8aa3b, v28
	v_mul_f32_e32 v32, 0xbfb8aa3b, v20
	v_exp_f32_e32 v33, v33
	v_mul_f32_e32 v36, 0xbfb8aa3b, v21
	v_exp_f32_e32 v32, v32
	v_exp_f32_e32 v37, v36
	v_add_f32_e32 v33, 1.0, v33
	v_rcp_f32_e32 v36, v33
	v_add_f32_e32 v32, 1.0, v32
	v_add_f32_e32 v33, 1.0, v37
	v_mul_f32_e32 v37, 0xbfb8aa3b, v29
	v_rcp_f32_e32 v32, v32
	v_rcp_f32_e32 v33, v33
	v_exp_f32_e32 v37, v37
	v_pk_mul_f32 v[20:21], v[20:21], s[42:43] op_sel_hi:[1,0]
	v_pk_fma_f32 v[48:49], v[10:11], v[114:115], v[14:15]
	v_pk_mul_f32 v[32:33], v[20:21], v[32:33]
	v_pk_mul_f32 v[20:21], v[28:29], s[42:43] op_sel_hi:[1,0]
	v_add_f32_e32 v28, 1.0, v37
	v_rcp_f32_e32 v37, v28
	v_pk_fma_f32 v[28:29], v[52:53], v[112:113], v[88:89]
	v_lshlrev_b32_e32 v113, 16, v207
	v_pk_fma_f32 v[28:29], v[54:55], v[104:105], v[28:29]
	v_lshlrev_b32_e32 v112, 16, v206
	v_pk_fma_f32 v[48:49], v[30:31], v[102:103], v[48:49]
	v_pk_fma_f32 v[28:29], v[100:101], v[40:41], v[28:29]
	v_and_b32_e32 v115, 0xffff0000, v207
	v_and_b32_e32 v114, 0xffff0000, v206
	v_pk_fma_f32 v[48:49], v[2:3], v[44:45], v[48:49]
	v_pk_fma_f32 v[28:29], v[106:107], v[112:113], v[28:29]
	v_pk_fma_f32 v[48:49], v[34:35], v[114:115], v[48:49]
	v_mul_f32_e32 v50, 0xbfb8aa3b, v28
	v_exp_f32_e32 v50, v50
	v_mul_f32_e32 v51, 0xbfb8aa3b, v48
	v_exp_f32_e32 v51, v51
	v_pk_mul_f32 v[36:37], v[20:21], v[36:37]
	v_add_f32_e32 v20, 1.0, v50
	v_mul_f32_e32 v50, 0xbfb8aa3b, v29
	v_add_f32_e32 v21, 1.0, v51
	v_exp_f32_e32 v51, v50
	v_mul_f32_e32 v50, 0xbfb8aa3b, v49
	v_exp_f32_e32 v75, v50
	v_rcp_f32_e32 v50, v21
	v_add_f32_e32 v21, 1.0, v51
	v_rcp_f32_e32 v20, v20
	v_rcp_f32_e32 v21, v21
	v_add_f32_e32 v51, 1.0, v75
; __device__ __forceinline__ unsigned pk2(float lo, float hi) { return f2bf(lo) | (f2bf(hi) << 16); }
; __device__ __forceinline__ void conv4x8(const bf16* proj, int t, int ch, const float* cw, const float* cb, float sc, float (&o)[4][8]) {
;     ...
;     for (int w = 0; w < 4; ++w) {
;         const f32x4 w0 = *(const f32x4*)(cw + w * 1024 + ch), w1 = *(const f32x4*)(cw + w * 1024 + ch + 4);
;         const float wv[8] = {w0[0], w0[1], w0[2], w0[3], w1[0], w1[1], w1[2], w1[3]};
; #pragma unroll
;         for (int j = 0; j < 4; ++j) { float xv[8]; unpack8(raw[j + w], xv);
; #pragma unroll
;             for (int e = 0; e < 8; ++e) o[j][e] += wv[e] * xv[e]; }
;     }
; #pragma unroll
;     for (int j = 0; j < 4; ++j)
; #pragma unroll
;         for (int e = 0; e < 8; ++e) o[j][e] = o[j][e] * sc * __builtin_amdgcn_rcpf(1.0f + __expf(-o[j][e]));
; }
; __device__ __forceinline__ u32x4 pack8(const float (&v)[8]) { u32x4 o; o.x = pk2(v[0], v[1]); o.y = pk2(v[2], v[3]); o.z = pk2(v[4], v[5]); o.w = pk2(v[6], v[7]); return o; }
; __device__ __forceinline__ void m1_phase(const Params& p, unsigned char* ldsg, int G) {
;     ...
;         conv4x8(PROJ, t0 + l0, 512 + h * HD + cgp * 8, p.convw, p.convb, 0.08838834764831845f, kk);
; #pragma unroll
;         for (int j = 0; j < 4; ++j) *(u32x4*)(QKC + (size_t)(t0 + l0 + j) * DM + 512 + h * HD + cgp * 8) = pack8(kk[j]);
	v_rcp_f32_e32 v51, v51
	v_pk_mul_f32 v[28:29], v[28:29], s[42:43] op_sel_hi:[1,0]
	v_and_b32_e32 v149, 0xffff0000, v209
	v_pk_mul_f32 v[28:29], v[28:29], v[20:21]
	v_pk_mul_f32 v[20:21], v[48:49], s[42:43] op_sel_hi:[1,0]
	v_bfe_u32 v79, v28, 16, 1
	v_pk_mul_f32 v[20:21], v[20:21], v[50:51]
	v_bfe_u32 v50, v37, 16, 1
	v_bfe_u32 v51, v36, 16, 1
	v_add3_u32 v75, v36, v51, s81
	v_add3_u32 v77, v37, v50, s81
	v_bfe_u32 v50, v32, 16, 1
	v_bfe_u32 v51, v33, 16, 1
	v_bfe_u32 v81, v29, 16, 1
	v_bfe_u32 v48, v21, 16, 1
	v_bfe_u32 v49, v20, 16, 1
	v_add3_u32 v81, v29, v81, s81
	v_add3_u32 v79, v28, v79, s81
	v_add3_u32 v51, v33, v51, s81
	v_add3_u32 v50, v32, v50, s81
	v_add3_u32 v49, v20, v49, s81
	v_add3_u32 v48, v21, v48, s81
	v_lshrrev_b32_e32 v147, 16, v50
	v_lshrrev_b32_e32 v148, 16, v51
	v_lshrrev_b32_e32 v50, 16, v79
	v_lshrrev_b32_e32 v51, 16, v81
	v_and_or_b32 v51, v48, s64, v51
	v_and_or_b32 v50, v49, s64, v50
	v_and_or_b32 v49, v77, s64, v148
	v_and_or_b32 v48, v75, s64, v147
	global_store_dwordx4 v[84:85], v[48:51], off offset:1024
	v_lshlrev_b32_e32 v85, 16, v209
	v_lshlrev_b32_e32 v84, 16, v208
	v_and_b32_e32 v148, 0xffff0000, v208
	v_pk_fma_f32 v[24:25], v[60:61], v[110:111], v[62:63]
	v_pk_fma_f32 v[48:49], v[18:19], v[108:109], v[22:23]
	v_pk_fma_f32 v[24:25], v[94:95], v[56:57], v[24:25]
	v_pk_fma_f32 v[48:49], v[38:39], v[58:59], v[48:49]
	v_pk_fma_f32 v[24:25], v[96:97], v[116:117], v[24:25]
	v_pk_fma_f32 v[48:49], v[42:43], v[82:83], v[48:49]
	v_pk_fma_f32 v[24:25], v[98:99], v[84:85], v[24:25]
	v_lshlrev_b32_e32 v111, 16, v211
	v_mul_f32_e32 v50, 0xbfb8aa3b, v24
	v_exp_f32_e32 v75, v50
	v_pk_fma_f32 v[50:51], v[46:47], v[148:149], v[48:49]
	v_lshlrev_b32_e32 v110, 16, v210
	v_mul_f32_e32 v49, 0xbfb8aa3b, v50
	v_add_f32_e32 v48, 1.0, v75
	v_exp_f32_e32 v49, v49
	v_mul_f32_e32 v75, 0xbfb8aa3b, v25
	v_exp_f32_e32 v75, v75
	v_rcp_f32_e32 v48, v48
	v_add_f32_e32 v49, 1.0, v49
	v_rcp_f32_e32 v108, v49
	v_add_f32_e32 v49, 1.0, v75
	v_mul_f32_e32 v75, 0xbfb8aa3b, v51
	v_rcp_f32_e32 v49, v49
	v_exp_f32_e32 v75, v75
	v_pk_mul_f32 v[24:25], v[24:25], s[42:43] op_sel_hi:[1,0]
	v_and_b32_e32 v151, 0xffff0000, v211
	v_pk_mul_f32 v[48:49], v[24:25], v[48:49]
	v_pk_mul_f32 v[24:25], v[50:51], s[42:43] op_sel_hi:[1,0]
	v_add_f32_e32 v50, 1.0, v75
	v_and_b32_e32 v150, 0xffff0000, v210
	v_pk_fma_f32 v[26:27], v[52:53], v[104:105], v[88:89]
	v_rcp_f32_e32 v109, v50
	v_pk_fma_f32 v[50:51], v[10:11], v[102:103], v[14:15]
	v_pk_fma_f32 v[26:27], v[54:55], v[40:41], v[26:27]
	v_pk_fma_f32 v[50:51], v[30:31], v[44:45], v[50:51]
	v_pk_fma_f32 v[26:27], v[100:101], v[112:113], v[26:27]
	v_pk_fma_f32 v[50:51], v[2:3], v[114:115], v[50:51]
	v_pk_fma_f32 v[26:27], v[106:107], v[110:111], v[26:27]
	v_pk_fma_f32 v[102:103], v[34:35], v[150:151], v[50:51]
	v_mul_f32_e32 v50, 0xbfb8aa3b, v26
	v_exp_f32_e32 v75, v50
	v_mul_f32_e32 v50, 0xbfb8aa3b, v102
	v_exp_f32_e32 v77, v50
	v_pk_mul_f32 v[50:51], v[24:25], v[108:109]
	v_add_f32_e32 v24, 1.0, v75
	v_mul_f32_e32 v75, 0xbfb8aa3b, v27
	v_add_f32_e32 v25, 1.0, v77
	v_exp_f32_e32 v75, v75
	v_mul_f32_e32 v77, 0xbfb8aa3b, v103
	v_exp_f32_e32 v77, v77
	v_rcp_f32_e32 v104, v25
	v_add_f32_e32 v25, 1.0, v75
	v_rcp_f32_e32 v24, v24
	v_rcp_f32_e32 v25, v25
	v_add_f32_e32 v75, 1.0, v77
	v_rcp_f32_e32 v105, v75
	v_pk_mul_f32 v[26:27], v[26:27], s[42:43] op_sel_hi:[1,0]
	v_bfe_u32 v79, v51, 16, 1
	v_pk_mul_f32 v[26:27], v[26:27], v[24:25]
	v_pk_mul_f32 v[24:25], v[102:103], s[42:43] op_sel_hi:[1,0]
	v_bfe_u32 v102, v48, 16, 1
	v_pk_mul_f32 v[24:25], v[24:25], v[104:105]
	v_bfe_u32 v103, v49, 16, 1
	v_bfe_u32 v104, v26, 16, 1
	v_bfe_u32 v105, v27, 16, 1
	v_bfe_u32 v75, v25, 16, 1
	v_bfe_u32 v77, v24, 16, 1
	v_bfe_u32 v81, v50, 16, 1
	v_add3_u32 v105, v27, v105, s81
	v_add3_u32 v104, v26, v104, s81
	v_add3_u32 v103, v49, v103, s81
	v_add3_u32 v102, v48, v102, s81
	v_add3_u32 v81, v50, v81, s81
	v_add3_u32 v79, v51, v79, s81
	v_add3_u32 v77, v24, v77, s81
	v_add3_u32 v75, v25, v75, s81
	v_lshrrev_b32_e32 v102, 16, v102
	v_lshrrev_b32_e32 v103, 16, v103
	v_lshrrev_b32_e32 v104, 16, v104
	v_lshrrev_b32_e32 v105, 16, v105
	v_pk_fma_f32 v[18:19], v[18:19], v[58:59], v[22:23]
	v_and_or_b32 v105, v75, s64, v105
	v_and_or_b32 v104, v77, s64, v104
	v_and_or_b32 v103, v79, s64, v103
	v_and_or_b32 v102, v81, s64, v102
	v_pk_fma_f32 v[56:57], v[60:61], v[56:57], v[62:63]
	v_pk_fma_f32 v[18:19], v[38:39], v[82:83], v[18:19]
	global_store_dwordx4 v[90:91], v[102:105], off offset:1024
	v_lshlrev_b32_e32 v91, 16, v213
	v_lshlrev_b32_e32 v90, 16, v212
	v_and_b32_e32 v5, 0xffff0000, v213
	v_and_b32_e32 v4, 0xffff0000, v212
	v_pk_fma_f32 v[22:23], v[94:95], v[116:117], v[56:57]
	v_pk_fma_f32 v[18:19], v[42:43], v[148:149], v[18:19]
	v_pk_fma_f32 v[22:23], v[96:97], v[84:85], v[22:23]
	v_pk_fma_f32 v[4:5], v[46:47], v[4:5], v[18:19]
	v_pk_fma_f32 v[22:23], v[98:99], v[90:91], v[22:23]
	v_mul_f32_e32 v19, 0xbfb8aa3b, v4
	v_mul_f32_e32 v56, 0xbfb8aa3b, v22
	v_exp_f32_e32 v19, v19
	v_mul_f32_e32 v38, 0xbfb8aa3b, v23
	v_exp_f32_e32 v56, v56
	v_exp_f32_e32 v39, v38
	v_add_f32_e32 v19, 1.0, v19
	v_rcp_f32_e32 v38, v19
	v_add_f32_e32 v18, 1.0, v56
	v_add_f32_e32 v19, 1.0, v39
	v_mul_f32_e32 v39, 0xbfb8aa3b, v5
	v_rcp_f32_e32 v18, v18
	v_rcp_f32_e32 v19, v19
	v_exp_f32_e32 v39, v39
	v_pk_mul_f32 v[22:23], v[22:23], s[42:43] op_sel_hi:[1,0]
	v_pk_fma_f32 v[40:41], v[52:53], v[40:41], v[88:89]
	v_pk_mul_f32 v[18:19], v[22:23], v[18:19]
	v_add_f32_e32 v22, 1.0, v39
	v_pk_fma_f32 v[10:11], v[10:11], v[44:45], v[14:15]
	v_pk_fma_f32 v[14:15], v[54:55], v[112:113], v[40:41]
	v_rcp_f32_e32 v39, v22
	v_lshlrev_b32_e32 v23, 16, v215
	v_lshlrev_b32_e32 v22, 16, v214
; __device__ __forceinline__ unsigned pk2(float lo, float hi) { return f2bf(lo) | (f2bf(hi) << 16); }
; __device__ __forceinline__ u32x4 pack8(const float (&v)[8]) { u32x4 o; o.x = pk2(v[0], v[1]); o.y = pk2(v[2], v[3]); o.z = pk2(v[4], v[5]); o.w = pk2(v[6], v[7]); return o; }
; __device__ __forceinline__ void m1_phase(const Params& p, unsigned char* ldsg, int G) {
;     ...
;         for (int j = 0; j < 4; ++j) *(u32x4*)(QKC + (size_t)(t0 + l0 + j) * DM + 512 + h * HD + cgp * 8) = pack8(kk[j]);
;         {
;             u32x4 rv[4];
; #pragma unroll
;             for (int j = 0; j < 4; ++j) rv[j] = *(const u32x4*)(PROJ + (size_t)(t0 + l0 + j) * NPROJ + 1024 + h * HD + cgp * 8);
; #pragma unroll
;             for (int e = 0; e < 8; ++e) {
;                 const unsigned sh = (e & 1) * 16;
;                 u32x2 o; o.x = ((rv[0][e >> 1] >> sh) & 0xffffu) | (((rv[1][e >> 1] >> sh) & 0xffffu) << 16); o.y = ((rv[2][e >> 1] >> sh) & 0xffffu) | (((rv[3][e >> 1] >> sh) & 0xffffu) << 16);
;                 *(u32x2*)(VT + tsw(cgp * 8 + e, l0)) = o;
;             }
;         }
;         __syncthreads();
;         {
;             const f32x4 w4 = *(const f32x4*)(sW + l0);
; #pragma unroll
;             for (int e = 0; e < 8; ++e) { u32x2 o; o.x = pk2(kk[0][e] * w4[0], kk[1][e] * w4[1]); o.y = pk2(kk[2][e] * w4[2], kk[3][e] * w4[3]); *(u32x2*)(KT + tsw(cgp * 8 + e, l0)) = o; }
	v_pk_fma_f32 v[10:11], v[30:31], v[114:115], v[10:11]
	v_pk_fma_f32 v[14:15], v[100:101], v[110:111], v[14:15]
	v_and_b32_e32 v7, 0xffff0000, v215
	v_and_b32_e32 v6, 0xffff0000, v214
	v_pk_fma_f32 v[2:3], v[2:3], v[150:151], v[10:11]
	v_pk_fma_f32 v[10:11], v[106:107], v[22:23], v[14:15]
	v_pk_fma_f32 v[2:3], v[34:35], v[6:7], v[2:3]
	v_mul_f32_e32 v6, 0xbfb8aa3b, v10
	v_exp_f32_e32 v6, v6
	v_mul_f32_e32 v7, 0xbfb8aa3b, v2
	v_exp_f32_e32 v7, v7
	v_pk_mul_f32 v[4:5], v[4:5], s[42:43] op_sel_hi:[1,0]
	s_nop 0
	v_pk_mul_f32 v[14:15], v[4:5], v[38:39]
	v_add_f32_e32 v4, 1.0, v6
	v_mul_f32_e32 v6, 0xbfb8aa3b, v11
	v_add_f32_e32 v5, 1.0, v7
	v_exp_f32_e32 v7, v6
	v_mul_f32_e32 v6, 0xbfb8aa3b, v3
	v_exp_f32_e32 v22, v6
	v_rcp_f32_e32 v6, v5
	v_add_f32_e32 v5, 1.0, v7
	v_rcp_f32_e32 v4, v4
	v_add_f32_e32 v7, 1.0, v22
	v_rcp_f32_e32 v5, v5
	v_rcp_f32_e32 v7, v7
	v_pk_mul_f32 v[10:11], v[10:11], s[42:43] op_sel_hi:[1,0]
	v_pk_mul_f32 v[2:3], v[2:3], s[42:43] op_sel_hi:[1,0]
	v_pk_mul_f32 v[10:11], v[10:11], v[4:5]
	v_pk_mul_f32 v[2:3], v[2:3], v[6:7]
	v_bfe_u32 v6, v15, 16, 1
	v_bfe_u32 v7, v14, 16, 1
	v_add3_u32 v22, v14, v7, s81
	v_add3_u32 v23, v15, v6, s81
	v_bfe_u32 v6, v18, 16, 1
	v_bfe_u32 v7, v19, 16, 1
	v_bfe_u32 v30, v10, 16, 1
	v_bfe_u32 v31, v11, 16, 1
	v_bfe_u32 v4, v3, 16, 1
	v_bfe_u32 v5, v2, 16, 1
	v_add3_u32 v31, v11, v31, s81
	v_add3_u32 v30, v10, v30, s81
	v_add3_u32 v7, v19, v7, s81
	v_add3_u32 v6, v18, v6, s81
	v_add3_u32 v5, v2, v5, s81
	v_add3_u32 v4, v3, v4, s81
	v_lshrrev_b32_e32 v34, 16, v6
	v_lshrrev_b32_e32 v35, 16, v7
	v_lshrrev_b32_e32 v6, 16, v30
	v_lshrrev_b32_e32 v7, 16, v31
	v_and_or_b32 v7, v4, s64, v7
	v_and_or_b32 v6, v5, s64, v6
	v_and_or_b32 v5, v23, s64, v35
	v_and_or_b32 v4, v22, s64, v34
	v_lshl_add_u64 v[22:23], s[56:57], 0, v[86:87]
	v_lshl_add_u64 v[22:23], v[22:23], 0, s[0:1]
	v_lshl_add_u64 v[22:23], v[22:23], 0, v[66:67]
	global_store_dwordx4 v[22:23], v[4:7], off offset:1024
	v_add_u32_e32 v34, 0x4800, v142
	v_mov_b32_e32 v35, v18
	s_lshl_b32 s0, s44, 14
	s_add_i32 s0, s0, s83
	v_and_b32_e32 v22, 0xffff, v216
	v_lshrrev_b32_e32 v4, 16, v216
	v_and_or_b32 v30, v220, s64, v4
	v_lshl_or_b32 v22, v220, 16, v22
	v_add_u32_e32 v38, s0, v127
	v_and_b32_e32 v23, 0xffff, v224
	v_lshrrev_b32_e32 v4, 16, v224
	v_lshl_or_b32 v23, v250, 16, v23
	v_and_or_b32 v31, v250, s64, v4
	v_and_b32_e32 v4, 0xffff, v217
	ds_write2_b64 v34, v[22:23], v[30:31] offset1:18
	v_lshl_or_b32 v22, v221, 16, v4
	v_and_b32_e32 v4, 0xffff, v225
	v_lshl_or_b32 v23, v251, 16, v4
	v_lshrrev_b32_e32 v4, 16, v217
	v_lshrrev_b32_e32 v5, 16, v225
	v_and_or_b32 v4, v221, s64, v4
	v_and_or_b32 v5, v251, s64, v5
	ds_write2_b64 v34, v[22:23], v[4:5] offset0:36 offset1:54
	v_and_b32_e32 v4, 0xffff, v218
	v_lshrrev_b32_e32 v6, 16, v218
	v_and_b32_e32 v5, 0xffff, v226
	v_and_or_b32 v22, v222, s64, v6
	v_lshrrev_b32_e32 v6, 16, v226
	v_lshl_or_b32 v4, v222, 16, v4
	v_lshl_or_b32 v5, v252, 16, v5
	v_and_or_b32 v23, v252, s64, v6
	ds_write2_b64 v34, v[4:5], v[22:23] offset0:72 offset1:90
	v_and_b32_e32 v4, 0xffff, v219
	v_and_b32_e32 v5, 0xffff, v227
	v_lshrrev_b32_e32 v6, 16, v219
	v_lshrrev_b32_e32 v7, 16, v227
	v_lshl_or_b32 v4, v223, 16, v4
	v_lshl_or_b32 v5, v253, 16, v5
	v_and_or_b32 v6, v223, s64, v6
	v_and_or_b32 v7, v253, s64, v7
	ds_write2_b64 v34, v[4:5], v[6:7] offset0:108 offset1:126
	s_waitcnt lgkmcnt(0)
	s_barrier
	ds_read_b128 v[4:7], v120 offset:36864
	v_mov_b32_e32 v22, v16
	v_mov_b32_e32 v23, v48
	v_mov_b32_e32 v34, v32
	v_mov_b32_e32 v48, v17
	s_waitcnt lgkmcnt(0)
	v_mov_b32_e32 v30, v4
	v_mov_b32_e32 v31, v6
	v_pk_mul_f32 v[22:23], v[22:23], v[30:31]
	v_mov_b32_e32 v6, v5
	v_pk_mul_f32 v[4:5], v[34:35], v[6:7]
	v_and_b32_sdwa v16, v23, v146 dst_sel:DWORD dst_unused:UNUSED_PAD src0_sel:WORD_1 src1_sel:DWORD
	v_and_b32_sdwa v18, v22, v146 dst_sel:DWORD dst_unused:UNUSED_PAD src0_sel:WORD_1 src1_sel:DWORD
	v_add3_u32 v18, v22, v18, s81
	v_add3_u32 v16, v23, v16, s81
	v_and_b32_sdwa v22, v5, v146 dst_sel:DWORD dst_unused:UNUSED_PAD src0_sel:WORD_1 src1_sel:DWORD
	v_and_b32_sdwa v23, v4, v146 dst_sel:DWORD dst_unused:UNUSED_PAD src0_sel:WORD_1 src1_sel:DWORD
	v_add3_u32 v5, v5, v22, s81
	v_add3_u32 v4, v4, v23, s81
	v_mov_b32_e32 v34, v36
	v_mov_b32_e32 v35, v14
	v_and_b32_e32 v5, 0xffff0000, v5
	v_and_b32_e32 v4, 0xffff0000, v4
	v_mov_b32_e32 v22, v12
	v_mov_b32_e32 v23, v50
	v_pk_mul_f32 v[34:35], v[34:35], v[6:7]
	v_or_b32_sdwa v5, v5, v16 dst_sel:DWORD dst_unused:UNUSED_PAD src0_sel:DWORD src1_sel:WORD_1
	v_or_b32_sdwa v4, v4, v18 dst_sel:DWORD dst_unused:UNUSED_PAD src0_sel:DWORD src1_sel:WORD_1
	v_pk_mul_f32 v[22:23], v[22:23], v[30:31]
	v_and_b32_sdwa v16, v35, v146 dst_sel:DWORD dst_unused:UNUSED_PAD src0_sel:WORD_1 src1_sel:DWORD
	v_and_b32_sdwa v18, v34, v146 dst_sel:DWORD dst_unused:UNUSED_PAD src0_sel:WORD_1 src1_sel:DWORD
	v_and_b32_sdwa v12, v23, v146 dst_sel:DWORD dst_unused:UNUSED_PAD src0_sel:WORD_1 src1_sel:DWORD
	v_and_b32_sdwa v14, v22, v146 dst_sel:DWORD dst_unused:UNUSED_PAD src0_sel:WORD_1 src1_sel:DWORD
	v_add3_u32 v16, v35, v16, s81
	v_add3_u32 v18, v34, v18, s81
	v_add3_u32 v14, v22, v14, s81
	v_add3_u32 v12, v23, v12, s81
	v_and_b32_e32 v16, 0xffff0000, v16
	v_and_b32_e32 v18, 0xffff0000, v18
	v_or_b32_sdwa v23, v16, v12 dst_sel:DWORD dst_unused:UNUSED_PAD src0_sel:DWORD src1_sel:WORD_1
	v_or_b32_sdwa v22, v18, v14 dst_sel:DWORD dst_unused:UNUSED_PAD src0_sel:DWORD src1_sel:WORD_1
	ds_write2_b64 v142, v[4:5], v[22:23] offset1:18
	v_pk_mul_f32 v[4:5], v[48:49], v[30:31]
	v_mov_b32_e32 v18, v33
	v_pk_mul_f32 v[16:17], v[18:19], v[6:7]
	v_and_b32_sdwa v12, v5, v146 dst_sel:DWORD dst_unused:UNUSED_PAD src0_sel:WORD_1 src1_sel:DWORD
; __device__ __forceinline__ unsigned pk2(float lo, float hi) { return f2bf(lo) | (f2bf(hi) << 16); }
; __device__ __forceinline__ void m1_phase(const Params& p, unsigned char* ldsg, int G) {
;     ...
;         {
;             const f32x4 w4 = *(const f32x4*)(sW + l0);
; #pragma unroll
;             for (int e = 0; e < 8; ++e) { u32x2 o; o.x = pk2(kk[0][e] * w4[0], kk[1][e] * w4[1]); o.y = pk2(kk[2][e] * w4[2], kk[3][e] * w4[3]); *(u32x2*)(KT + tsw(cgp * 8 + e, l0)) = o; }
;         }
;         __syncthreads();
	v_and_b32_sdwa v14, v4, v146 dst_sel:DWORD dst_unused:UNUSED_PAD src0_sel:WORD_1 src1_sel:DWORD
	v_add3_u32 v4, v4, v14, s81
	v_add3_u32 v5, v5, v12, s81
	v_and_b32_sdwa v12, v17, v146 dst_sel:DWORD dst_unused:UNUSED_PAD src0_sel:WORD_1 src1_sel:DWORD
	v_and_b32_sdwa v14, v16, v146 dst_sel:DWORD dst_unused:UNUSED_PAD src0_sel:WORD_1 src1_sel:DWORD
	v_add3_u32 v12, v17, v12, s81
	v_add3_u32 v14, v16, v14, s81
	v_and_b32_e32 v12, 0xffff0000, v12
	v_and_b32_e32 v14, 0xffff0000, v14
	v_mov_b32_e32 v50, v13
	v_or_b32_sdwa v5, v12, v5 dst_sel:DWORD dst_unused:UNUSED_PAD src0_sel:DWORD src1_sel:WORD_1
	v_or_b32_sdwa v4, v14, v4 dst_sel:DWORD dst_unused:UNUSED_PAD src0_sel:DWORD src1_sel:WORD_1
	v_pk_mul_f32 v[12:13], v[50:51], v[30:31]
	v_mov_b32_e32 v14, v37
	v_pk_mul_f32 v[14:15], v[14:15], v[6:7]
	v_and_b32_sdwa v16, v13, v146 dst_sel:DWORD dst_unused:UNUSED_PAD src0_sel:WORD_1 src1_sel:DWORD
	v_and_b32_sdwa v17, v12, v146 dst_sel:DWORD dst_unused:UNUSED_PAD src0_sel:WORD_1 src1_sel:DWORD
	v_add3_u32 v12, v12, v17, s81
	v_add3_u32 v13, v13, v16, s81
	v_and_b32_sdwa v16, v15, v146 dst_sel:DWORD dst_unused:UNUSED_PAD src0_sel:WORD_1 src1_sel:DWORD
	v_and_b32_sdwa v17, v14, v146 dst_sel:DWORD dst_unused:UNUSED_PAD src0_sel:WORD_1 src1_sel:DWORD
	v_add3_u32 v15, v15, v16, s81
	v_add3_u32 v14, v14, v17, s81
	v_and_b32_e32 v15, 0xffff0000, v15
	v_and_b32_e32 v14, 0xffff0000, v14
	v_or_b32_sdwa v13, v15, v13 dst_sel:DWORD dst_unused:UNUSED_PAD src0_sel:DWORD src1_sel:WORD_1
	v_or_b32_sdwa v12, v14, v12 dst_sel:DWORD dst_unused:UNUSED_PAD src0_sel:DWORD src1_sel:WORD_1
	ds_write2_b64 v142, v[4:5], v[12:13] offset0:36 offset1:54
	v_mov_b32_e32 v4, v8
	v_mov_b32_e32 v5, v26
	v_pk_mul_f32 v[4:5], v[4:5], v[30:31]
	v_mov_b32_e32 v12, v28
	v_mov_b32_e32 v13, v10
	v_pk_mul_f32 v[12:13], v[12:13], v[6:7]
	v_and_b32_sdwa v8, v5, v146 dst_sel:DWORD dst_unused:UNUSED_PAD src0_sel:WORD_1 src1_sel:DWORD
	v_and_b32_sdwa v10, v4, v146 dst_sel:DWORD dst_unused:UNUSED_PAD src0_sel:WORD_1 src1_sel:DWORD
	v_add3_u32 v4, v4, v10, s81
	v_add3_u32 v5, v5, v8, s81
	v_and_b32_sdwa v8, v13, v146 dst_sel:DWORD dst_unused:UNUSED_PAD src0_sel:WORD_1 src1_sel:DWORD
	v_and_b32_sdwa v10, v12, v146 dst_sel:DWORD dst_unused:UNUSED_PAD src0_sel:WORD_1 src1_sel:DWORD
	v_add3_u32 v8, v13, v8, s81
	v_add3_u32 v10, v12, v10, s81
	v_mov_b32_e32 v14, v20
	v_mov_b32_e32 v15, v2
	v_and_b32_e32 v8, 0xffff0000, v8
	v_and_b32_e32 v10, 0xffff0000, v10
	v_mov_b32_e32 v12, v0
	v_mov_b32_e32 v13, v24
	v_pk_mul_f32 v[14:15], v[14:15], v[6:7]
	v_or_b32_sdwa v5, v8, v5 dst_sel:DWORD dst_unused:UNUSED_PAD src0_sel:DWORD src1_sel:WORD_1
	v_or_b32_sdwa v4, v10, v4 dst_sel:DWORD dst_unused:UNUSED_PAD src0_sel:DWORD src1_sel:WORD_1
	v_pk_mul_f32 v[12:13], v[12:13], v[30:31]
	v_and_b32_sdwa v8, v15, v146 dst_sel:DWORD dst_unused:UNUSED_PAD src0_sel:WORD_1 src1_sel:DWORD
	v_and_b32_sdwa v10, v14, v146 dst_sel:DWORD dst_unused:UNUSED_PAD src0_sel:WORD_1 src1_sel:DWORD
	v_and_b32_sdwa v0, v13, v146 dst_sel:DWORD dst_unused:UNUSED_PAD src0_sel:WORD_1 src1_sel:DWORD
	v_and_b32_sdwa v2, v12, v146 dst_sel:DWORD dst_unused:UNUSED_PAD src0_sel:WORD_1 src1_sel:DWORD
	v_add3_u32 v8, v15, v8, s81
	v_add3_u32 v10, v14, v10, s81
	v_add3_u32 v2, v12, v2, s81
	v_add3_u32 v0, v13, v0, s81
	v_and_b32_e32 v8, 0xffff0000, v8
	v_and_b32_e32 v10, 0xffff0000, v10
	v_or_b32_sdwa v13, v8, v0 dst_sel:DWORD dst_unused:UNUSED_PAD src0_sel:DWORD src1_sel:WORD_1
	v_or_b32_sdwa v12, v10, v2 dst_sel:DWORD dst_unused:UNUSED_PAD src0_sel:DWORD src1_sel:WORD_1
	v_mov_b32_e32 v26, v9
	ds_write2_b64 v142, v[4:5], v[12:13] offset0:72 offset1:90
	v_pk_mul_f32 v[4:5], v[26:27], v[30:31]
	v_mov_b32_e32 v10, v29
	v_pk_mul_f32 v[8:9], v[10:11], v[6:7]
	v_and_b32_sdwa v0, v5, v146 dst_sel:DWORD dst_unused:UNUSED_PAD src0_sel:WORD_1 src1_sel:DWORD
	v_and_b32_sdwa v2, v4, v146 dst_sel:DWORD dst_unused:UNUSED_PAD src0_sel:WORD_1 src1_sel:DWORD
	v_add3_u32 v2, v4, v2, s81
	v_add3_u32 v0, v5, v0, s81
	v_and_b32_sdwa v4, v9, v146 dst_sel:DWORD dst_unused:UNUSED_PAD src0_sel:WORD_1 src1_sel:DWORD
	v_and_b32_sdwa v5, v8, v146 dst_sel:DWORD dst_unused:UNUSED_PAD src0_sel:WORD_1 src1_sel:DWORD
	v_add3_u32 v4, v9, v4, s81
	v_add3_u32 v5, v8, v5, s81
	v_and_b32_e32 v4, 0xffff0000, v4
	v_and_b32_e32 v8, 0xffff0000, v5
	v_mov_b32_e32 v24, v1
	v_or_b32_sdwa v5, v4, v0 dst_sel:DWORD dst_unused:UNUSED_PAD src0_sel:DWORD src1_sel:WORD_1
	v_or_b32_sdwa v4, v8, v2 dst_sel:DWORD dst_unused:UNUSED_PAD src0_sel:DWORD src1_sel:WORD_1
	v_pk_mul_f32 v[0:1], v[24:25], v[30:31]
	v_mov_b32_e32 v2, v21
	v_pk_mul_f32 v[2:3], v[2:3], v[6:7]
	v_and_b32_sdwa v6, v1, v146 dst_sel:DWORD dst_unused:UNUSED_PAD src0_sel:WORD_1 src1_sel:DWORD
	v_and_b32_sdwa v7, v0, v146 dst_sel:DWORD dst_unused:UNUSED_PAD src0_sel:WORD_1 src1_sel:DWORD
	v_add3_u32 v0, v0, v7, s81
	v_add3_u32 v1, v1, v6, s81
	v_and_b32_sdwa v6, v3, v146 dst_sel:DWORD dst_unused:UNUSED_PAD src0_sel:WORD_1 src1_sel:DWORD
	v_and_b32_sdwa v7, v2, v146 dst_sel:DWORD dst_unused:UNUSED_PAD src0_sel:WORD_1 src1_sel:DWORD
	v_add3_u32 v3, v3, v6, s81
	v_add3_u32 v2, v2, v7, s81
	v_and_b32_e32 v3, 0xffff0000, v3
	v_and_b32_e32 v2, 0xffff0000, v2
	v_or_b32_sdwa v1, v3, v1 dst_sel:DWORD dst_unused:UNUSED_PAD src0_sel:DWORD src1_sel:WORD_1
	v_or_b32_sdwa v0, v2, v0 dst_sel:DWORD dst_unused:UNUSED_PAD src0_sel:DWORD src1_sel:WORD_1
	ds_write2_b64 v142, v[4:5], v[0:1] offset0:108 offset1:126
	s_waitcnt lgkmcnt(0)
	s_barrier
; __device__ __forceinline__ unsigned pk2(float lo, float hi) { return f2bf(lo) | (f2bf(hi) << 16); }
; __device__ __forceinline__ void m1_phase(const Params& p, unsigned char* ldsg, int G) {
;     ...
;         {
;             bf16x8 av[2][2];
; #pragma unroll
;             for (int mi = 0; mi < 2; ++mi)
; #pragma unroll
;                 for (int ks = 0; ks < 2; ++ks) av[mi][ks] = *(const bf16x8*)(VT + tsw(16 * (2 * hw + mi) + fr, ks * 32 + fq * 8));
; #pragma unroll
;             for (int nt = 0; nt < 8; ++nt) {
;                 bf16x8 bk[2];
; #pragma unroll
;                 for (int ks = 0; ks < 2; ++ks) bk[ks] = *(const bf16x8*)(KT + tsw(16 * nt + fr, ks * 32 + fq * 8));
; #pragma unroll
;                 for (int mi = 0; mi < 2; ++mi) {
;                     f32x4 acc = (f32x4){0.f, 0.f, 0.f, 0.f};
; #pragma unroll
;                     for (int ks = 0; ks < 2; ++ks) acc = __builtin_amdgcn_mfma_f32_16x16x32_bf16(bk[ks], av[mi][ks], acc, 0, 0, 0);
;                     u32x2 o; o.x = pk2(acc[0], acc[1]); o.y = pk2(acc[2], acc[3]);
;                     { const int vd = 16 * (2 * hw + mi) + fr; *(u32x2*)(DCB + ((size_t)((h * 64 + (vd >> 1)) * NCH + c) << 8) + (vd & 1) * 128 + 16 * nt + fq * 4) = o; }
;                 }
;             }
	ds_read_b128 v[16:19], v125
	ds_read_b128 v[20:23], v126
	ds_read_b128 v[12:15], v121 offset:18432
	ds_read_b128 v[8:11], v122 offset:18432
	ds_read_b128 v[4:7], v123 offset:18432
	ds_read_b128 v[0:3], v124 offset:18432
	ds_read_b128 v[24:27], v125 offset:9216
	s_waitcnt lgkmcnt(4)
	v_mfma_f32_16x16x32_bf16 v[28:31], v[16:19], v[12:15], 0
	ds_read_b128 v[32:35], v126 offset:9216
	v_ashrrev_i32_e32 v39, 31, v38
	s_waitcnt lgkmcnt(4)
	v_mfma_f32_16x16x32_bf16 v[28:31], v[20:23], v[8:11], v[28:31]
	s_nop 7
	v_bfe_u32 v36, v28, 16, 1
	v_add3_u32 v28, v28, v36, s81
	v_bfe_u32 v36, v29, 16, 1
	v_lshrrev_b32_e32 v28, 16, v28
	v_add3_u32 v29, v29, v36, s81
	v_and_or_b32 v36, v29, s64, v28
	v_bfe_u32 v28, v30, 16, 1
	v_add3_u32 v28, v30, v28, s81
	v_bfe_u32 v29, v31, 16, 1
	v_lshrrev_b32_e32 v28, 16, v28
	v_add3_u32 v29, v31, v29, s81
	v_and_or_b32 v37, v29, s64, v28
	s_waitcnt lgkmcnt(3)
	v_mfma_f32_16x16x32_bf16 v[28:31], v[16:19], v[4:7], 0
	v_lshlrev_b64 v[16:17], 9, v[38:39]
	v_lshl_add_u64 v[16:17], v[70:71], 0, v[16:17]
	global_store_dwordx2 v[16:17], v[36:37], off
	s_waitcnt lgkmcnt(2)
	v_mfma_f32_16x16x32_bf16 v[18:21], v[20:23], v[0:3], v[28:31]
	ds_read_b128 v[36:39], v130
	s_nop 1
	ds_read_b128 v[28:31], v129
	s_nop 3
	v_bfe_u32 v22, v18, 16, 1
	v_add3_u32 v18, v18, v22, s81
	v_bfe_u32 v22, v19, 16, 1
	v_lshrrev_b32_e32 v18, 16, v18
	v_add3_u32 v19, v19, v22, s81
	v_and_or_b32 v40, v19, s64, v18
	v_bfe_u32 v18, v20, 16, 1
	v_bfe_u32 v19, v21, 16, 1
	v_add3_u32 v18, v20, v18, s81
	v_add3_u32 v19, v21, v19, s81
	s_waitcnt lgkmcnt(0)
	v_mfma_f32_16x16x32_bf16 v[20:23], v[28:31], v[12:15], 0
	v_lshrrev_b32_e32 v18, 16, v18
	v_and_or_b32 v41, v19, s64, v18
	v_add_u32_e32 v18, s0, v128
	v_mfma_f32_16x16x32_bf16 v[20:23], v[36:39], v[8:11], v[20:23]
	v_ashrrev_i32_e32 v19, 31, v18
	v_lshlrev_b64 v[18:19], 9, v[18:19]
	v_lshl_add_u64 v[18:19], v[70:71], 0, v[18:19]
	global_store_dwordx2 v[18:19], v[40:41], off
	v_mfma_f32_16x16x32_bf16 v[28:31], v[28:31], v[4:7], 0
	s_nop 2
	v_bfe_u32 v40, v20, 16, 1
	v_add3_u32 v20, v20, v40, s81
	v_bfe_u32 v40, v21, 16, 1
	v_lshrrev_b32_e32 v20, 16, v20
	v_add3_u32 v21, v21, v40, s81
	v_and_or_b32 v20, v21, s64, v20
	v_bfe_u32 v21, v22, 16, 1
	v_add3_u32 v21, v22, v21, s81
	v_bfe_u32 v22, v23, 16, 1
	v_lshrrev_b32_e32 v21, 16, v21
	v_add3_u32 v22, v23, v22, s81
	v_and_or_b32 v21, v22, s64, v21
	global_store_dwordx2 v[16:17], v[20:21], off offset:32
	v_mfma_f32_16x16x32_bf16 v[20:23], v[36:39], v[0:3], v[28:31]
	s_nop 7
	v_bfe_u32 v28, v20, 16, 1
	v_add3_u32 v20, v20, v28, s81
	ds_read_b128 v[28:31], v131
	v_bfe_u32 v36, v21, 16, 1
	v_add3_u32 v21, v21, v36, s81
	ds_read_b128 v[36:39], v132
	v_lshrrev_b32_e32 v20, 16, v20
	v_and_or_b32 v20, v21, s64, v20
	v_bfe_u32 v21, v22, 16, 1
	s_waitcnt lgkmcnt(1)
	v_mfma_f32_16x16x32_bf16 v[40:43], v[28:31], v[12:15], 0
	v_add3_u32 v21, v22, v21, s81
	v_bfe_u32 v22, v23, 16, 1
	v_lshrrev_b32_e32 v21, 16, v21
	v_add3_u32 v22, v23, v22, s81
	v_and_or_b32 v21, v22, s64, v21
	global_store_dwordx2 v[18:19], v[20:21], off offset:32
	s_waitcnt lgkmcnt(0)
	v_mfma_f32_16x16x32_bf16 v[20:23], v[36:39], v[8:11], v[40:43]
	v_mfma_f32_16x16x32_bf16 v[28:31], v[28:31], v[4:7], 0
	s_nop 6
	v_bfe_u32 v40, v20, 16, 1
	v_add3_u32 v20, v20, v40, s81
	v_bfe_u32 v40, v21, 16, 1
	v_lshrrev_b32_e32 v20, 16, v20
	v_add3_u32 v21, v21, v40, s81
	v_and_or_b32 v20, v21, s64, v20
	v_bfe_u32 v21, v22, 16, 1
	v_add3_u32 v21, v22, v21, s81
	v_bfe_u32 v22, v23, 16, 1
	v_lshrrev_b32_e32 v21, 16, v21
	v_add3_u32 v22, v23, v22, s81
	v_and_or_b32 v21, v22, s64, v21
	global_store_dwordx2 v[16:17], v[20:21], off offset:64
	v_mfma_f32_16x16x32_bf16 v[20:23], v[36:39], v[0:3], v[28:31]
	s_nop 7
	v_bfe_u32 v28, v20, 16, 1
	v_add3_u32 v20, v20, v28, s81
	ds_read_b128 v[28:31], v133
	v_bfe_u32 v36, v21, 16, 1
	v_add3_u32 v21, v21, v36, s81
	ds_read_b128 v[36:39], v134
	v_lshrrev_b32_e32 v20, 16, v20
	v_and_or_b32 v20, v21, s64, v20
	v_bfe_u32 v21, v22, 16, 1
	s_waitcnt lgkmcnt(1)
	v_mfma_f32_16x16x32_bf16 v[40:43], v[28:31], v[12:15], 0
	v_add3_u32 v21, v22, v21, s81
	v_bfe_u32 v22, v23, 16, 1
	v_lshrrev_b32_e32 v21, 16, v21
	v_add3_u32 v22, v23, v22, s81
	v_and_or_b32 v21, v22, s64, v21
	global_store_dwordx2 v[18:19], v[20:21], off offset:64
	s_waitcnt lgkmcnt(0)
; __device__ __forceinline__ unsigned pk2(float lo, float hi) { return f2bf(lo) | (f2bf(hi) << 16); }
; __device__ __forceinline__ float bf2f(unsigned b) { return __uint_as_float(b << 16); }
; __device__ __forceinline__ void m1_phase(const Params& p, unsigned char* ldsg, int G) {
;     ...
;             for (int nt = 0; nt < 8; ++nt) {
;                 bf16x8 bk[2];
; #pragma unroll
;                 for (int ks = 0; ks < 2; ++ks) bk[ks] = *(const bf16x8*)(KT + tsw(16 * nt + fr, ks * 32 + fq * 8));
; #pragma unroll
;                 for (int mi = 0; mi < 2; ++mi) {
;                     f32x4 acc = (f32x4){0.f, 0.f, 0.f, 0.f};
; #pragma unroll
;                     for (int ks = 0; ks < 2; ++ks) acc = __builtin_amdgcn_mfma_f32_16x16x32_bf16(bk[ks], av[mi][ks], acc, 0, 0, 0);
;                     u32x2 o; o.x = pk2(acc[0], acc[1]); o.y = pk2(acc[2], acc[3]);
;                     { const int vd = 16 * (2 * hw + mi) + fr; *(u32x2*)(DCB + ((size_t)((h * 64 + (vd >> 1)) * NCH + c) << 8) + (vd & 1) * 128 + 16 * nt + fq * 4) = o; }
;                 }
;             }
;             if (htid < 128) { float s = 0.f;
; #pragma unroll 8
;                 for (int l = 0; l < 64; ++l) s += bf2f(KT[htid * TP + l]);
;                 DN[(size_t)(h * NCH + c) * 128 + htid] = s; }
	v_mfma_f32_16x16x32_bf16 v[20:23], v[36:39], v[8:11], v[40:43]
	v_mfma_f32_16x16x32_bf16 v[28:31], v[28:31], v[4:7], 0
	s_nop 6
	v_bfe_u32 v40, v20, 16, 1
	v_add3_u32 v20, v20, v40, s81
	v_bfe_u32 v40, v21, 16, 1
	v_lshrrev_b32_e32 v20, 16, v20
	v_add3_u32 v21, v21, v40, s81
	v_and_or_b32 v20, v21, s64, v20
	v_bfe_u32 v21, v22, 16, 1
	v_add3_u32 v21, v22, v21, s81
	v_bfe_u32 v22, v23, 16, 1
	v_lshrrev_b32_e32 v21, 16, v21
	v_add3_u32 v22, v23, v22, s81
	v_and_or_b32 v21, v22, s64, v21
	global_store_dwordx2 v[16:17], v[20:21], off offset:96
	v_mfma_f32_16x16x32_bf16 v[20:23], v[36:39], v[0:3], v[28:31]
	s_nop 7
	v_bfe_u32 v28, v20, 16, 1
	v_add3_u32 v20, v20, v28, s81
	v_bfe_u32 v28, v21, 16, 1
	v_lshrrev_b32_e32 v20, 16, v20
	v_add3_u32 v21, v21, v28, s81
	v_and_or_b32 v20, v21, s64, v20
	v_bfe_u32 v21, v22, 16, 1
	v_mfma_f32_16x16x32_bf16 v[28:31], v[24:27], v[12:15], 0
	v_add3_u32 v21, v22, v21, s81
	v_bfe_u32 v22, v23, 16, 1
	v_lshrrev_b32_e32 v21, 16, v21
	v_add3_u32 v22, v23, v22, s81
	v_and_or_b32 v21, v22, s64, v21
	global_store_dwordx2 v[18:19], v[20:21], off offset:96
	v_mfma_f32_16x16x32_bf16 v[20:23], v[32:35], v[8:11], v[28:31]
	v_mfma_f32_16x16x32_bf16 v[24:27], v[24:27], v[4:7], 0
	s_nop 6
	v_bfe_u32 v28, v20, 16, 1
	v_add3_u32 v20, v20, v28, s81
	v_bfe_u32 v28, v21, 16, 1
	v_lshrrev_b32_e32 v20, 16, v20
	v_add3_u32 v21, v21, v28, s81
	v_and_or_b32 v20, v21, s64, v20
	v_bfe_u32 v21, v22, 16, 1
	v_add3_u32 v21, v22, v21, s81
	v_bfe_u32 v22, v23, 16, 1
	v_lshrrev_b32_e32 v21, 16, v21
	v_add3_u32 v22, v23, v22, s81
	v_and_or_b32 v21, v22, s64, v21
	global_store_dwordx2 v[16:17], v[20:21], off offset:128
	v_mfma_f32_16x16x32_bf16 v[20:23], v[32:35], v[0:3], v[24:27]
	s_nop 7
	v_bfe_u32 v24, v20, 16, 1
	v_add3_u32 v20, v20, v24, s81
	ds_read_b128 v[24:27], v135
	v_bfe_u32 v28, v21, 16, 1
	v_add3_u32 v21, v21, v28, s81
	ds_read_b128 v[28:31], v136
	v_lshrrev_b32_e32 v20, 16, v20
	v_and_or_b32 v20, v21, s64, v20
	v_bfe_u32 v21, v22, 16, 1
	s_waitcnt lgkmcnt(1)
	v_mfma_f32_16x16x32_bf16 v[32:35], v[24:27], v[12:15], 0
	v_add3_u32 v21, v22, v21, s81
	v_bfe_u32 v22, v23, 16, 1
	v_lshrrev_b32_e32 v21, 16, v21
	v_add3_u32 v22, v23, v22, s81
	v_and_or_b32 v21, v22, s64, v21
	global_store_dwordx2 v[18:19], v[20:21], off offset:128
	s_waitcnt lgkmcnt(0)
	v_mfma_f32_16x16x32_bf16 v[20:23], v[28:31], v[8:11], v[32:35]
	v_mfma_f32_16x16x32_bf16 v[24:27], v[24:27], v[4:7], 0
	s_nop 6
	v_bfe_u32 v32, v20, 16, 1
	v_add3_u32 v20, v20, v32, s81
	v_bfe_u32 v32, v21, 16, 1
	v_lshrrev_b32_e32 v20, 16, v20
	v_add3_u32 v21, v21, v32, s81
	v_and_or_b32 v20, v21, s64, v20
	v_bfe_u32 v21, v22, 16, 1
	v_add3_u32 v21, v22, v21, s81
	v_bfe_u32 v22, v23, 16, 1
	v_lshrrev_b32_e32 v21, 16, v21
	v_add3_u32 v22, v23, v22, s81
	v_and_or_b32 v21, v22, s64, v21
	global_store_dwordx2 v[16:17], v[20:21], off offset:160
	v_mfma_f32_16x16x32_bf16 v[20:23], v[28:31], v[0:3], v[24:27]
	s_nop 7
	v_bfe_u32 v24, v20, 16, 1
	v_add3_u32 v20, v20, v24, s81
	ds_read_b128 v[24:27], v137
	v_bfe_u32 v28, v21, 16, 1
	v_add3_u32 v21, v21, v28, s81
	ds_read_b128 v[28:31], v138
	v_lshrrev_b32_e32 v20, 16, v20
	v_and_or_b32 v20, v21, s64, v20
	v_bfe_u32 v21, v22, 16, 1
	s_waitcnt lgkmcnt(1)
	v_mfma_f32_16x16x32_bf16 v[32:35], v[24:27], v[12:15], 0
	v_add3_u32 v21, v22, v21, s81
	v_bfe_u32 v22, v23, 16, 1
	v_lshrrev_b32_e32 v21, 16, v21
	v_add3_u32 v22, v23, v22, s81
	v_and_or_b32 v21, v22, s64, v21
	global_store_dwordx2 v[18:19], v[20:21], off offset:160
	s_waitcnt lgkmcnt(0)
	v_mfma_f32_16x16x32_bf16 v[20:23], v[28:31], v[8:11], v[32:35]
	v_mfma_f32_16x16x32_bf16 v[24:27], v[24:27], v[4:7], 0
	s_nop 6
	v_bfe_u32 v32, v20, 16, 1
	v_add3_u32 v20, v20, v32, s81
	v_bfe_u32 v32, v21, 16, 1
	v_lshrrev_b32_e32 v20, 16, v20
	v_add3_u32 v21, v21, v32, s81
	v_and_or_b32 v20, v21, s64, v20
	v_bfe_u32 v21, v22, 16, 1
	v_add3_u32 v21, v22, v21, s81
	v_bfe_u32 v22, v23, 16, 1
	v_lshrrev_b32_e32 v21, 16, v21
	v_add3_u32 v22, v23, v22, s81
	v_and_or_b32 v21, v22, s64, v21
	global_store_dwordx2 v[16:17], v[20:21], off offset:192
	v_mfma_f32_16x16x32_bf16 v[20:23], v[28:31], v[0:3], v[24:27]
	s_nop 7
	v_bfe_u32 v24, v20, 16, 1
	v_add3_u32 v20, v20, v24, s81
	ds_read_b128 v[24:27], v139
	v_bfe_u32 v28, v21, 16, 1
	v_add3_u32 v21, v21, v28, s81
	ds_read_b128 v[28:31], v140
	s_waitcnt lgkmcnt(1)
	v_mfma_f32_16x16x32_bf16 v[12:15], v[24:27], v[12:15], 0
	v_lshrrev_b32_e32 v20, 16, v20
	v_and_or_b32 v20, v21, s64, v20
	v_bfe_u32 v21, v22, 16, 1
	v_mfma_f32_16x16x32_bf16 v[4:7], v[24:27], v[4:7], 0
	v_add3_u32 v21, v22, v21, s81
	v_bfe_u32 v22, v23, 16, 1
	v_lshrrev_b32_e32 v21, 16, v21
	s_waitcnt lgkmcnt(0)
	v_mfma_f32_16x16x32_bf16 v[8:11], v[28:31], v[8:11], v[12:15]
	v_add3_u32 v22, v23, v22, s81
	v_and_or_b32 v21, v22, s64, v21
	global_store_dwordx2 v[18:19], v[20:21], off offset:192
	v_mfma_f32_16x16x32_bf16 v[0:3], v[28:31], v[0:3], v[4:7]
	s_nop 3
	v_bfe_u32 v12, v8, 16, 1
	s_nop 2
	v_bfe_u32 v4, v0, 16, 1
	v_add3_u32 v8, v8, v12, s81
	v_bfe_u32 v12, v9, 16, 1
	v_add3_u32 v0, v0, v4, s81
	v_bfe_u32 v4, v1, 16, 1
	v_lshrrev_b32_e32 v8, 16, v8
	v_add3_u32 v9, v9, v12, s81
	v_lshrrev_b32_e32 v0, 16, v0
	v_add3_u32 v1, v1, v4, s81
	v_and_or_b32 v8, v9, s64, v8
	v_bfe_u32 v9, v10, 16, 1
	v_and_or_b32 v0, v1, s64, v0
	v_bfe_u32 v1, v2, 16, 1
	v_add3_u32 v9, v10, v9, s81
	v_bfe_u32 v10, v11, 16, 1
	v_add3_u32 v1, v2, v1, s81
	v_bfe_u32 v2, v3, 16, 1
	v_lshrrev_b32_e32 v9, 16, v9
	v_add3_u32 v10, v11, v10, s81
	v_lshrrev_b32_e32 v1, 16, v1
	v_add3_u32 v2, v3, v2, s81
	v_and_or_b32 v9, v10, s64, v9
	v_and_or_b32 v1, v2, s64, v1
	global_store_dwordx2 v[16:17], v[8:9], off offset:224
	global_store_dwordx2 v[18:19], v[0:1], off offset:224
	s_and_saveexec_b64 s[0:1], s[20:21]
	s_cbranch_execz .LBB0_610
	v_mov_b32_e32 v0, 0
	s_mov_b32 s22, 0
